# residual epilogues: second batch of x loads issued before waiting on the first
# speedup vs baseline: 1.0106x; 1.0042x over previous
; #define ER_LOAD(ai) _Pragma("unroll") for (int m = 0; m < 4; ++m) _Pragma("unroll") for (int bj = 0; bj < 2; ++bj) xv[m][bj] = *(const u32x4*)(x16 + base + (size_t)((ai) * HALF + m * 16) * D + bj * HALF);
; #define ER_ADD(ai) _Pragma("unroll") for (int m = 0; m < 4; ++m) _Pragma("unroll") for (int bj = 0; bj < 2; ++bj) { const u32x4 w = xv[m][bj]; \
;             acc[ai][bj][m][0] += (f32x4){h_lo(w.x), h_hi(w.x), h_lo(w.y), h_hi(w.y)}; acc[ai][bj][m][1] += (f32x4){h_lo(w.z), h_hi(w.z), h_lo(w.w), h_hi(w.w)}; }
;     __device__ __forceinline__ void operator()(Acc& acc, const Unit& u, int wr, int wc, int fr, int fq) const {
;     ...
;         ER_LOAD(0); ER_ADD(0); ER_LOAD(1); ER_STORE(0); ER_ADD(1); ER_STORE(1);
.LBB0_237:
	v_lshl_add_u32 v138, s52, 8, v162
	v_ashrrev_i32_e32 v139, 31, v138
	v_lshl_or_b32 v140, s49, 8, v164
	v_lshlrev_b64 v[142:143], 12, v[138:139]
	v_ashrrev_i32_e32 v141, 31, v140
	v_lshl_add_u64 v[142:143], s[6:7], 0, v[142:143]
	v_lshl_add_u64 v[146:147], v[140:141], 1, v[142:143]
	v_add_co_u32_e32 v144, vcc, 0x10000, v146
	global_load_dwordx4 v[148:151], v[146:147], off
	global_load_dwordx4 v[152:155], v[146:147], off offset:256
	v_addc_co_u32_e32 v145, vcc, 0, v147, vcc
	global_load_dwordx4 v[156:159], v[144:145], off
	global_load_dwordx4 v[166:169], v[144:145], off offset:256
	v_add_co_u32_e32 v142, vcc, 0x20000, v146
	s_nop 1
	v_addc_co_u32_e32 v143, vcc, 0, v147, vcc
	global_load_dwordx4 v[170:173], v[142:143], off
	global_load_dwordx4 v[178:181], v[142:143], off offset:256
	v_add_co_u32_e32 v140, vcc, 0x30000, v146
	s_nop 1
	v_addc_co_u32_e32 v141, vcc, 0, v147, vcc
	global_load_dwordx4 v[182:185], v[140:141], off
	global_load_dwordx4 v[186:189], v[140:141], off offset:256
	s_waitcnt vmcnt(4)
	v_lshlrev_b32_e32 v174, 16, v150
	v_and_b32_e32 v175, 0xffff0000, v150
	v_lshlrev_b32_e32 v150, 16, v151
	v_and_b32_e32 v151, 0xffff0000, v151
	v_lshlrev_b32_e32 v160, 16, v148
	v_and_b32_e32 v161, 0xffff0000, v148
	v_lshlrev_b32_e32 v148, 16, v149
	v_and_b32_e32 v149, 0xffff0000, v149
	v_lshlrev_b32_e32 v190, 16, v152
	v_and_b32_e32 v191, 0xffff0000, v152
	v_lshlrev_b32_e32 v152, 16, v153
	v_and_b32_e32 v153, 0xffff0000, v153
	v_pk_add_f32 v[200:201], v[122:123], v[150:151]
	v_lshlrev_b32_e32 v122, 16, v167
	v_and_b32_e32 v123, 0xffff0000, v167
	v_lshlrev_b32_e32 v192, 16, v154
	v_and_b32_e32 v193, 0xffff0000, v154
	v_lshlrev_b32_e32 v154, 16, v155
	v_and_b32_e32 v155, 0xffff0000, v155
	v_pk_add_f32 v[194:195], v[126:127], v[148:149]
	v_pk_add_f32 v[198:199], v[124:125], v[160:161]
	v_pk_add_f32 v[208:209], v[118:119], v[152:153]
	v_pk_add_f32 v[190:191], v[116:117], v[190:191]
	v_lshlrev_b32_e32 v116, 16, v158
	v_and_b32_e32 v117, 0xffff0000, v158
	v_lshlrev_b32_e32 v118, 16, v159
	v_and_b32_e32 v119, 0xffff0000, v159
	v_lshlrev_b32_e32 v124, 16, v168
	v_and_b32_e32 v125, 0xffff0000, v168
	v_lshlrev_b32_e32 v126, 16, v169
	v_and_b32_e32 v127, 0xffff0000, v169
	v_pk_add_f32 v[158:159], v[102:103], v[122:123]
	v_pk_add_f32 v[174:175], v[120:121], v[174:175]
	v_pk_add_f32 v[210:211], v[114:115], v[154:155]
	v_lshlrev_b32_e32 v120, 16, v166
	v_and_b32_e32 v121, 0xffff0000, v166
	v_pk_add_f32 v[216:217], v[106:107], v[118:119]
	v_pk_add_f32 v[154:155], v[90:91], v[126:127]
	v_pk_add_f32 v[220:221], v[88:89], v[124:125]
	v_pk_add_f32 v[160:161], v[100:101], v[120:121]
	v_pk_add_f32 v[192:193], v[112:113], v[192:193]
	v_lshlrev_b32_e32 v112, 16, v156
	v_and_b32_e32 v113, 0xffff0000, v156
	v_lshlrev_b32_e32 v114, 16, v157
	v_and_b32_e32 v115, 0xffff0000, v157
	v_pk_add_f32 v[212:213], v[110:111], v[114:115]
	v_pk_add_f32 v[218:219], v[104:105], v[116:117]
	v_pk_add_f32 v[214:215], v[108:109], v[112:113]
	v_cvt_pk_bf16_f32 v166, v198, v199
	v_cvt_pk_bf16_f32 v167, v194, v195
	v_cvt_pk_bf16_f32 v168, v174, v175
	v_cvt_pk_bf16_f32 v169, v200, v201
	s_waitcnt vmcnt(3)
	v_lshlrev_b32_e32 v102, 16, v173
	v_and_b32_e32 v103, 0xffff0000, v173
	v_lshlrev_b32_e32 v88, 16, v170
	v_and_b32_e32 v89, 0xffff0000, v170
	v_lshlrev_b32_e32 v90, 16, v171
	v_and_b32_e32 v91, 0xffff0000, v171
	v_pk_add_f32 v[118:119], v[94:95], v[102:103]
	v_add_co_u32_e32 v102, vcc, s77, v146
	v_lshlrev_b32_e32 v100, 16, v172
	v_and_b32_e32 v101, 0xffff0000, v172
	v_pk_add_f32 v[148:149], v[98:99], v[90:91]
	v_pk_add_f32 v[152:153], v[96:97], v[88:89]
	s_waitcnt vmcnt(2)
	v_lshlrev_b32_e32 v88, 16, v178
	v_and_b32_e32 v89, 0xffff0000, v178
	v_lshlrev_b32_e32 v90, 16, v179
	v_and_b32_e32 v91, 0xffff0000, v179
	v_addc_co_u32_e32 v103, vcc, 0, v147, vcc
	v_pk_add_f32 v[126:127], v[92:93], v[100:101]
	v_pk_add_f32 v[120:121], v[82:83], v[90:91]
	v_pk_add_f32 v[150:151], v[80:81], v[88:89]
	global_load_dwordx4 v[92:95], v[102:103], off
	global_load_dwordx4 v[88:91], v[102:103], off offset:256
	v_lshlrev_b32_e32 v80, 16, v180
	v_and_b32_e32 v81, 0xffff0000, v180
	v_lshlrev_b32_e32 v82, 16, v181
	v_and_b32_e32 v83, 0xffff0000, v181
	v_add_co_u32_e32 v100, vcc, s76, v146
	v_pk_add_f32 v[124:125], v[74:75], v[82:83]
	v_pk_add_f32 v[156:157], v[72:73], v[80:81]
	s_waitcnt vmcnt(3)
	v_lshlrev_b32_e32 v72, 16, v182
	v_and_b32_e32 v73, 0xffff0000, v182
	v_lshlrev_b32_e32 v74, 16, v183
	v_and_b32_e32 v75, 0xffff0000, v183
	v_addc_co_u32_e32 v101, vcc, 0, v147, vcc
	v_pk_add_f32 v[110:111], v[86:87], v[74:75]
	v_pk_add_f32 v[116:117], v[84:85], v[72:73]
	global_load_dwordx4 v[84:87], v[100:101], off
	global_load_dwordx4 v[80:83], v[100:101], off offset:256
	v_lshlrev_b32_e32 v72, 16, v184
	v_and_b32_e32 v73, 0xffff0000, v184
	v_lshlrev_b32_e32 v74, 16, v185
	v_and_b32_e32 v75, 0xffff0000, v185
	v_add_co_u32_e32 v98, vcc, s56, v146
	v_pk_add_f32 v[114:115], v[78:79], v[74:75]
	v_pk_add_f32 v[122:123], v[76:77], v[72:73]
	s_waitcnt vmcnt(4)
; #define ER_LOAD(ai) _Pragma("unroll") for (int m = 0; m < 4; ++m) _Pragma("unroll") for (int bj = 0; bj < 2; ++bj) xv[m][bj] = *(const u32x4*)(x16 + base + (size_t)((ai) * HALF + m * 16) * D + bj * HALF);
; #define ER_ADD(ai) _Pragma("unroll") for (int m = 0; m < 4; ++m) _Pragma("unroll") for (int bj = 0; bj < 2; ++bj) { const u32x4 w = xv[m][bj]; \
;             acc[ai][bj][m][0] += (f32x4){h_lo(w.x), h_hi(w.x), h_lo(w.y), h_hi(w.y)}; acc[ai][bj][m][1] += (f32x4){h_lo(w.z), h_hi(w.z), h_lo(w.w), h_hi(w.w)}; }
;     __device__ __forceinline__ void operator()(Acc& acc, const Unit& u, int wr, int wc, int fr, int fq) const {
;     ...
;         ER_LOAD(0); ER_ADD(0); ER_LOAD(1); ER_STORE(0); ER_ADD(1); ER_STORE(1);
	v_lshlrev_b32_e32 v72, 16, v186
	v_and_b32_e32 v73, 0xffff0000, v186
	v_lshlrev_b32_e32 v74, 16, v187
	v_and_b32_e32 v75, 0xffff0000, v187
	v_addc_co_u32_e32 v99, vcc, 0, v147, vcc
	v_pk_add_f32 v[104:105], v[70:71], v[74:75]
	v_pk_add_f32 v[108:109], v[68:69], v[72:73]
	global_load_dwordx4 v[76:79], v[98:99], off
	global_load_dwordx4 v[72:75], v[98:99], off offset:256
	v_add_co_u32_e32 v96, vcc, s68, v146
	v_lshlrev_b32_e32 v68, 16, v188
	v_and_b32_e32 v69, 0xffff0000, v188
	v_lshlrev_b32_e32 v70, 16, v189
	v_and_b32_e32 v71, 0xffff0000, v189
	v_addc_co_u32_e32 v97, vcc, 0, v147, vcc
	v_pk_add_f32 v[106:107], v[66:67], v[70:71]
	v_pk_add_f32 v[112:113], v[64:65], v[68:69]
	global_load_dwordx4 v[68:71], v[96:97], off
	global_load_dwordx4 v[64:67], v[96:97], off offset:256
	s_nop 0
	global_store_dwordx4 v[146:147], v[166:169], off
	s_nop 1
	v_mul_f32_e32 v166, v199, v199
	v_mul_f32_e32 v167, v195, v195
	v_fmac_f32_e32 v166, v198, v198
	v_fmac_f32_e32 v167, v194, v194
	v_add_f32_e32 v166, v166, v167
	v_mul_f32_e32 v167, v175, v175
	v_fmac_f32_e32 v167, v174, v174
	v_add_f32_e32 v166, v167, v166
	v_mul_f32_e32 v167, v201, v201
	v_fmac_f32_e32 v167, v200, v200
	v_add_f32_e32 v170, v167, v166
	v_cvt_pk_bf16_f32 v166, v190, v191
	v_cvt_pk_bf16_f32 v167, v208, v209
	v_cvt_pk_bf16_f32 v168, v192, v193
	v_cvt_pk_bf16_f32 v169, v210, v211
	global_store_dwordx4 v[146:147], v[166:169], off offset:256
	v_mul_f32_e32 v146, v191, v191
	v_mul_f32_e32 v147, v209, v209
	v_fmac_f32_e32 v146, v190, v190
	v_fmac_f32_e32 v147, v208, v208
	v_add_f32_e32 v146, v146, v147
	v_mul_f32_e32 v147, v193, v193
	v_fmac_f32_e32 v147, v192, v192
	v_add_f32_e32 v146, v147, v146
	v_mul_f32_e32 v147, v211, v211
	v_fmac_f32_e32 v147, v210, v210
	v_cvt_pk_bf16_f32 v166, v214, v215
	v_add_f32_e32 v146, v147, v146
	v_cvt_pk_bf16_f32 v167, v212, v213
	v_cvt_pk_bf16_f32 v168, v218, v219
	v_cvt_pk_bf16_f32 v169, v216, v217
	global_store_dwordx4 v[144:145], v[166:169], off
	v_mul_f32_e32 v147, v215, v215
	v_fmac_f32_e32 v147, v214, v214
	v_mul_f32_e32 v166, v213, v213
	v_fmac_f32_e32 v166, v212, v212
	v_add_f32_e32 v147, v147, v166
	v_mul_f32_e32 v166, v219, v219
	v_fmac_f32_e32 v166, v218, v218
	v_add_f32_e32 v147, v166, v147
	v_mul_f32_e32 v166, v217, v217
	v_fmac_f32_e32 v166, v216, v216
	v_add_f32_e32 v147, v166, v147
	v_cvt_pk_bf16_f32 v166, v160, v161
	v_cvt_pk_bf16_f32 v167, v158, v159
	v_cvt_pk_bf16_f32 v168, v220, v221
	v_cvt_pk_bf16_f32 v169, v154, v155
	global_store_dwordx4 v[144:145], v[166:169], off offset:256
	v_mul_f32_e32 v144, v161, v161
	v_mul_f32_e32 v145, v159, v159
	v_fmac_f32_e32 v144, v160, v160
	v_fmac_f32_e32 v145, v158, v158
	v_add_f32_e32 v144, v144, v145
	v_mul_f32_e32 v145, v221, v221
	v_fmac_f32_e32 v145, v220, v220
	v_add_f32_e32 v144, v145, v144
	v_mul_f32_e32 v145, v155, v155
	v_fmac_f32_e32 v145, v154, v154
	v_add_f32_e32 v144, v145, v144
	v_add_f32_e32 v144, v147, v144
	v_mul_f32_e32 v145, v153, v153
	v_mul_f32_e32 v147, v149, v149
	v_cvt_pk_bf16_f32 v160, v126, v127
	v_fmac_f32_e32 v145, v152, v152
	v_fmac_f32_e32 v147, v148, v148
	v_mul_f32_e32 v127, v127, v127
	v_cvt_pk_bf16_f32 v161, v118, v119
	v_add_f32_e32 v145, v145, v147
	v_fmac_f32_e32 v127, v126, v126
	v_mul_f32_e32 v119, v119, v119
	v_add_f32_e32 v126, v127, v145
	v_fmac_f32_e32 v119, v118, v118
	v_cvt_pk_bf16_f32 v158, v152, v153
	v_add_f32_e32 v118, v119, v126
	v_cvt_pk_bf16_f32 v153, v120, v121
	v_mul_f32_e32 v119, v151, v151
	v_mul_f32_e32 v121, v121, v121
	v_fmac_f32_e32 v119, v150, v150
	v_fmac_f32_e32 v121, v120, v120
	v_mul_f32_e32 v120, v157, v157
	v_add_f32_e32 v119, v119, v121
	v_fmac_f32_e32 v120, v156, v156
	v_add_f32_e32 v119, v120, v119
	v_mul_f32_e32 v120, v125, v125
	v_cvt_pk_bf16_f32 v155, v124, v125
	v_fmac_f32_e32 v120, v124, v124
	v_cvt_pk_bf16_f32 v124, v116, v117
	v_cvt_pk_bf16_f32 v125, v110, v111
	v_mul_f32_e32 v117, v117, v117
	v_mul_f32_e32 v111, v111, v111
	v_fmac_f32_e32 v117, v116, v116
	v_fmac_f32_e32 v111, v110, v110
	v_add_f32_e32 v110, v117, v111
	v_mul_f32_e32 v111, v123, v123
	v_fmac_f32_e32 v111, v122, v122
	v_add_f32_e32 v110, v111, v110
	v_mul_f32_e32 v111, v115, v115
	v_cvt_pk_bf16_f32 v127, v114, v115
	v_fmac_f32_e32 v111, v114, v114
	v_cvt_pk_bf16_f32 v114, v108, v109
	v_cvt_pk_bf16_f32 v115, v104, v105
	v_mul_f32_e32 v109, v109, v109
	v_mul_f32_e32 v105, v105, v105
	v_fmac_f32_e32 v109, v108, v108
	v_fmac_f32_e32 v105, v104, v104
	v_add_f32_e32 v104, v109, v105
	v_mul_f32_e32 v105, v113, v113
	v_fmac_f32_e32 v105, v112, v112
	v_add_f32_e32 v104, v105, v104
	v_mul_f32_e32 v105, v107, v107
	v_fmac_f32_e32 v105, v106, v106
	v_add_f32_e32 v110, v111, v110
	v_add_f32_e32 v104, v105, v104
	v_cvt_pk_bf16_f32 v117, v106, v107
	v_add_f32_e32 v106, v110, v104
	s_waitcnt vmcnt(11)
	v_lshlrev_b32_e32 v104, 16, v92
	v_and_b32_e32 v105, 0xffff0000, v92
	v_lshlrev_b32_e32 v92, 16, v93
	v_and_b32_e32 v93, 0xffff0000, v93
	v_pk_add_f32 v[62:63], v[62:63], v[92:93]
	v_lshlrev_b32_e32 v92, 16, v94
	v_and_b32_e32 v93, 0xffff0000, v94
	v_pk_add_f32 v[56:57], v[56:57], v[92:93]
	s_waitcnt vmcnt(10)
	v_lshlrev_b32_e32 v92, 16, v88
	v_and_b32_e32 v93, 0xffff0000, v88
	v_lshlrev_b32_e32 v88, 16, v89
	v_and_b32_e32 v89, 0xffff0000, v89
	v_pk_add_f32 v[50:51], v[50:51], v[88:89]
	v_lshlrev_b32_e32 v88, 16, v90
	v_and_b32_e32 v89, 0xffff0000, v90
	v_pk_add_f32 v[40:41], v[40:41], v[88:89]
	s_waitcnt vmcnt(9)
	v_lshlrev_b32_e32 v88, 16, v84
	v_and_b32_e32 v89, 0xffff0000, v84
	v_lshlrev_b32_e32 v84, 16, v85
	v_and_b32_e32 v85, 0xffff0000, v85
	v_pk_add_f32 v[54:55], v[54:55], v[84:85]
	v_lshlrev_b32_e32 v84, 16, v86
	v_and_b32_e32 v85, 0xffff0000, v86
	v_pk_add_f32 v[44:45], v[44:45], v[84:85]
	s_waitcnt vmcnt(8)
; #define ER_LOAD(ai) _Pragma("unroll") for (int m = 0; m < 4; ++m) _Pragma("unroll") for (int bj = 0; bj < 2; ++bj) xv[m][bj] = *(const u32x4*)(x16 + base + (size_t)((ai) * HALF + m * 16) * D + bj * HALF);
; #define ER_ADD(ai) _Pragma("unroll") for (int m = 0; m < 4; ++m) _Pragma("unroll") for (int bj = 0; bj < 2; ++bj) { const u32x4 w = xv[m][bj]; \
;             acc[ai][bj][m][0] += (f32x4){h_lo(w.x), h_hi(w.x), h_lo(w.y), h_hi(w.y)}; acc[ai][bj][m][1] += (f32x4){h_lo(w.z), h_hi(w.z), h_lo(w.w), h_hi(w.w)}; }
;     __device__ __forceinline__ void operator()(Acc& acc, const Unit& u, int wr, int wc, int fr, int fq) const {
;     ...
;         ER_LOAD(0); ER_ADD(0); ER_LOAD(1); ER_STORE(0); ER_ADD(1); ER_STORE(1);
	v_lshlrev_b32_e32 v84, 16, v80
	v_and_b32_e32 v85, 0xffff0000, v80
	v_lshlrev_b32_e32 v80, 16, v81
	v_and_b32_e32 v81, 0xffff0000, v81
	v_pk_add_f32 v[34:35], v[34:35], v[80:81]
	v_lshlrev_b32_e32 v80, 16, v82
	v_and_b32_e32 v81, 0xffff0000, v82
	v_pk_add_f32 v[24:25], v[24:25], v[80:81]
	s_waitcnt vmcnt(7)
	v_lshlrev_b32_e32 v80, 16, v76
	v_and_b32_e32 v81, 0xffff0000, v76
	v_lshlrev_b32_e32 v76, 16, v77
	v_and_b32_e32 v77, 0xffff0000, v77
	v_pk_add_f32 v[38:39], v[38:39], v[76:77]
	v_lshlrev_b32_e32 v76, 16, v78
	v_and_b32_e32 v77, 0xffff0000, v78
	v_pk_add_f32 v[28:29], v[28:29], v[76:77]
	s_waitcnt vmcnt(6)
	v_lshlrev_b32_e32 v76, 16, v72
	v_and_b32_e32 v77, 0xffff0000, v72
	v_lshlrev_b32_e32 v72, 16, v73
	v_and_b32_e32 v73, 0xffff0000, v73
	v_pk_add_f32 v[18:19], v[18:19], v[72:73]
	v_lshlrev_b32_e32 v72, 16, v74
	v_and_b32_e32 v73, 0xffff0000, v74
	v_lshlrev_b32_e32 v74, 16, v75
	v_and_b32_e32 v75, 0xffff0000, v75
	v_pk_add_f32 v[74:75], v[10:11], v[74:75]
	v_pk_add_f32 v[72:73], v[8:9], v[72:73]
	s_waitcnt vmcnt(5)
	v_lshlrev_b32_e32 v10, 16, v68
	v_and_b32_e32 v11, 0xffff0000, v68
	v_lshlrev_b32_e32 v8, 16, v69
	v_and_b32_e32 v9, 0xffff0000, v69
	v_pk_add_f32 v[8:9], v[22:23], v[8:9]
	v_pk_add_f32 v[20:21], v[20:21], v[10:11]
	v_lshlrev_b32_e32 v10, 16, v70
	v_and_b32_e32 v11, 0xffff0000, v70
	v_lshlrev_b32_e32 v22, 16, v71
	v_and_b32_e32 v23, 0xffff0000, v71
	v_pk_add_f32 v[14:15], v[14:15], v[22:23]
	v_pk_add_f32 v[22:23], v[12:13], v[10:11]
	s_waitcnt vmcnt(4)
	v_lshlrev_b32_e32 v10, 16, v64
	v_and_b32_e32 v11, 0xffff0000, v64
	v_lshlrev_b32_e32 v12, 16, v65
	v_and_b32_e32 v13, 0xffff0000, v65
	v_pk_add_f32 v[4:5], v[4:5], v[10:11]
	v_lshlrev_b32_e32 v10, 16, v66
	v_and_b32_e32 v11, 0xffff0000, v66
	v_pk_add_f32 v[60:61], v[60:61], v[104:105]
	v_lshlrev_b32_e32 v94, 16, v95
	v_and_b32_e32 v95, 0xffff0000, v95
	v_pk_add_f32 v[6:7], v[6:7], v[12:13]
	v_lshlrev_b32_e32 v12, 16, v67
	v_and_b32_e32 v13, 0xffff0000, v67
	v_pk_add_f32 v[0:1], v[0:1], v[10:11]
	v_cvt_pk_bf16_f32 v10, v60, v61
	v_cvt_pk_bf16_f32 v11, v62, v63
	v_pk_add_f32 v[58:59], v[58:59], v[94:95]
	v_pk_add_f32 v[2:3], v[2:3], v[12:13]
	v_cvt_pk_bf16_f32 v12, v56, v57
	v_cvt_pk_bf16_f32 v13, v58, v59
	global_store_dwordx4 v[102:103], v[10:13], off
	v_pk_add_f32 v[48:49], v[48:49], v[92:93]
	v_lshlrev_b32_e32 v90, 16, v91
	v_mul_f32_e32 v10, v61, v61
	v_mul_f32_e32 v11, v63, v63
	v_fmac_f32_e32 v10, v60, v60
	v_fmac_f32_e32 v11, v62, v62
	v_add_f32_e32 v10, v10, v11
	v_mul_f32_e32 v11, v57, v57
	v_fmac_f32_e32 v11, v56, v56
	v_add_f32_e32 v10, v11, v10
	v_mul_f32_e32 v11, v59, v59
	v_fmac_f32_e32 v11, v58, v58
	v_and_b32_e32 v91, 0xffff0000, v91
	v_add_f32_e32 v56, v11, v10
	v_cvt_pk_bf16_f32 v10, v48, v49
	v_cvt_pk_bf16_f32 v11, v50, v51
	v_pk_add_f32 v[42:43], v[42:43], v[90:91]
	v_cvt_pk_bf16_f32 v12, v40, v41
	v_pk_add_f32 v[52:53], v[52:53], v[88:89]
	v_cvt_pk_bf16_f32 v13, v42, v43
	global_store_dwordx4 v[102:103], v[10:13], off offset:256
	v_lshlrev_b32_e32 v86, 16, v87
	v_and_b32_e32 v87, 0xffff0000, v87
	v_mul_f32_e32 v10, v49, v49
	v_mul_f32_e32 v11, v51, v51
	v_fmac_f32_e32 v10, v48, v48
	v_fmac_f32_e32 v11, v50, v50
	v_add_f32_e32 v10, v10, v11
	v_mul_f32_e32 v11, v41, v41
	v_fmac_f32_e32 v11, v40, v40
	v_add_f32_e32 v10, v11, v10
	v_mul_f32_e32 v11, v43, v43
	v_fmac_f32_e32 v11, v42, v42
	v_add_f32_e32 v10, v11, v10
	v_add_f32_e32 v40, v56, v10
	v_cvt_pk_bf16_f32 v10, v52, v53
	v_cvt_pk_bf16_f32 v11, v54, v55
	v_pk_add_f32 v[46:47], v[46:47], v[86:87]
	v_cvt_pk_bf16_f32 v12, v44, v45
	v_pk_add_f32 v[32:33], v[32:33], v[84:85]
	v_cvt_pk_bf16_f32 v13, v46, v47
	global_store_dwordx4 v[100:101], v[10:13], off
	v_lshlrev_b32_e32 v82, 16, v83
	v_and_b32_e32 v83, 0xffff0000, v83
	v_mul_f32_e32 v10, v53, v53
	v_mul_f32_e32 v11, v55, v55
	v_fmac_f32_e32 v10, v52, v52
	v_fmac_f32_e32 v11, v54, v54
	v_add_f32_e32 v10, v10, v11
	v_mul_f32_e32 v11, v45, v45
	v_fmac_f32_e32 v11, v44, v44
	v_add_f32_e32 v10, v11, v10
	v_mul_f32_e32 v11, v47, v47
	v_fmac_f32_e32 v11, v46, v46
	v_add_f32_e32 v41, v11, v10
	v_cvt_pk_bf16_f32 v10, v32, v33
	v_cvt_pk_bf16_f32 v11, v34, v35
	v_pk_add_f32 v[26:27], v[26:27], v[82:83]
	v_cvt_pk_bf16_f32 v12, v24, v25
	v_pk_add_f32 v[36:37], v[36:37], v[80:81]
	v_cvt_pk_bf16_f32 v13, v26, v27
	global_store_dwordx4 v[100:101], v[10:13], off offset:256
	v_lshlrev_b32_e32 v78, 16, v79
	v_and_b32_e32 v79, 0xffff0000, v79
	v_mul_f32_e32 v10, v33, v33
	v_mul_f32_e32 v11, v35, v35
	v_fmac_f32_e32 v10, v32, v32
	v_fmac_f32_e32 v11, v34, v34
	v_add_f32_e32 v10, v10, v11
	v_mul_f32_e32 v11, v25, v25
	v_fmac_f32_e32 v11, v24, v24
	v_add_f32_e32 v10, v11, v10
	v_mul_f32_e32 v11, v27, v27
	v_fmac_f32_e32 v11, v26, v26
	v_add_f32_e32 v10, v11, v10
	v_add_f32_e32 v24, v41, v10
	v_cvt_pk_bf16_f32 v10, v36, v37
	v_cvt_pk_bf16_f32 v11, v38, v39
	v_pk_add_f32 v[30:31], v[30:31], v[78:79]
	v_cvt_pk_bf16_f32 v12, v28, v29
	v_pk_add_f32 v[16:17], v[16:17], v[76:77]
	v_cvt_pk_bf16_f32 v13, v30, v31
	global_store_dwordx4 v[98:99], v[10:13], off
; __device__ __forceinline__ void ssq_add(ssq_t* p, float v) { __hip_atomic_fetch_add(p, ssq_fix(v), __ATOMIC_RELAXED, __HIP_MEMORY_SCOPE_AGENT); }
; #define ER_LOAD(ai) _Pragma("unroll") for (int m = 0; m < 4; ++m) _Pragma("unroll") for (int bj = 0; bj < 2; ++bj) xv[m][bj] = *(const u32x4*)(x16 + base + (size_t)((ai) * HALF + m * 16) * D + bj * HALF);
; #define ER_ADD(ai) _Pragma("unroll") for (int m = 0; m < 4; ++m) _Pragma("unroll") for (int bj = 0; bj < 2; ++bj) { const u32x4 w = xv[m][bj]; \
;             acc[ai][bj][m][0] += (f32x4){h_lo(w.x), h_hi(w.x), h_lo(w.y), h_hi(w.y)}; acc[ai][bj][m][1] += (f32x4){h_lo(w.z), h_hi(w.z), h_lo(w.w), h_hi(w.w)}; }
;     __device__ __forceinline__ void operator()(Acc& acc, const Unit& u, int wr, int wc, int fr, int fq) const {
;     ...
;         ER_LOAD(0); ER_ADD(0); ER_LOAD(1); ER_STORE(0); ER_ADD(1); ER_STORE(1);
;     ...
; #pragma unroll
;         for (int q = 0; q < 8; ++q) { ssv[q] += __shfl_xor(ssv[q], 16); }
; #pragma unroll
;         for (int q = 0; q < 8; ++q) { ssv[q] += __shfl_xor(ssv[q], 32); }
;         if (fq == 0) {
; #pragma unroll
;             for (int q = 0; q < 8; ++q) ssq_add(ssq_out + row0 + (q >> 2) * HALF + (q & 3) * 16, ssv[q]);
	v_add_f32_e32 v119, v120, v119
	v_add_f32_e32 v146, v170, v146
	v_mul_f32_e32 v10, v37, v37
	v_mul_f32_e32 v11, v39, v39
	v_fmac_f32_e32 v10, v36, v36
	v_fmac_f32_e32 v11, v38, v38
	v_add_f32_e32 v10, v10, v11
	v_mul_f32_e32 v11, v29, v29
	v_fmac_f32_e32 v11, v28, v28
	v_add_f32_e32 v10, v11, v10
	v_mul_f32_e32 v11, v31, v31
	v_fmac_f32_e32 v11, v30, v30
	v_add_f32_e32 v25, v11, v10
	v_cvt_pk_bf16_f32 v10, v16, v17
	v_cvt_pk_bf16_f32 v11, v18, v19
	v_cvt_pk_bf16_f32 v12, v72, v73
	v_cvt_pk_bf16_f32 v13, v74, v75
	global_store_dwordx4 v[98:99], v[10:13], off offset:256
	v_add_f32_e32 v118, v118, v119
	v_cvt_pk_bf16_f32 v159, v148, v149
	global_store_dwordx4 v[142:143], v[158:161], off
	v_mul_f32_e32 v10, v17, v17
	v_mul_f32_e32 v11, v19, v19
	v_fmac_f32_e32 v10, v16, v16
	v_fmac_f32_e32 v11, v18, v18
	v_add_f32_e32 v10, v10, v11
	v_mul_f32_e32 v11, v73, v73
	v_fmac_f32_e32 v11, v72, v72
	v_add_f32_e32 v10, v11, v10
	v_mul_f32_e32 v11, v75, v75
	v_fmac_f32_e32 v11, v74, v74
	v_add_f32_e32 v10, v11, v10
	v_add_f32_e32 v16, v25, v10
	v_cvt_pk_bf16_f32 v10, v20, v21
	v_cvt_pk_bf16_f32 v11, v8, v9
	v_cvt_pk_bf16_f32 v12, v22, v23
	v_cvt_pk_bf16_f32 v13, v14, v15
	global_store_dwordx4 v[96:97], v[10:13], off
	v_mul_f32_e32 v9, v9, v9
	v_fmac_f32_e32 v9, v8, v8
	v_mul_f32_e32 v10, v21, v21
	v_fmac_f32_e32 v10, v20, v20
	v_add_f32_e32 v8, v10, v9
	v_mul_f32_e32 v9, v23, v23
	v_fmac_f32_e32 v9, v22, v22
	v_add_f32_e32 v8, v9, v8
	v_mul_f32_e32 v9, v15, v15
	v_fmac_f32_e32 v9, v14, v14
	v_and_b32_e32 v10, 64, v204
	v_add_f32_e32 v8, v9, v8
	v_xor_b32_e32 v9, 16, v204
	v_add_u32_e32 v13, 64, v10
	v_cvt_pk_bf16_f32 v22, v4, v5
	v_mul_f32_e32 v5, v5, v5
	v_cmp_lt_i32_e32 vcc, v9, v13
	v_fmac_f32_e32 v5, v4, v4
	v_mul_f32_e32 v4, v7, v7
	v_cndmask_b32_e32 v9, v204, v9, vcc
	v_fmac_f32_e32 v4, v6, v6
	v_lshlrev_b32_e32 v9, 2, v9
	v_add_f32_e32 v4, v5, v4
	v_mul_f32_e32 v5, v1, v1
	ds_bpermute_b32 v10, v9, v146
	ds_bpermute_b32 v11, v9, v144
	ds_bpermute_b32 v12, v9, v118
	v_fmac_f32_e32 v5, v0, v0
	v_add_f32_e32 v4, v5, v4
	v_mul_f32_e32 v5, v3, v3
	v_fmac_f32_e32 v5, v2, v2
	v_add_f32_e32 v4, v5, v4
	v_add_f32_e32 v14, v8, v4
	s_waitcnt lgkmcnt(2)
	v_add_f32_e32 v4, v146, v10
	s_waitcnt lgkmcnt(1)
	v_add_f32_e32 v5, v144, v11
	s_waitcnt lgkmcnt(0)
	v_add_f32_e32 v8, v118, v12
	ds_bpermute_b32 v10, v9, v106
	ds_bpermute_b32 v11, v9, v40
	ds_bpermute_b32 v12, v9, v24
	ds_bpermute_b32 v15, v9, v16
	ds_bpermute_b32 v17, v9, v14
	s_waitcnt lgkmcnt(4)
	v_add_f32_e32 v9, v106, v10
	s_waitcnt lgkmcnt(3)
	v_add_f32_e32 v10, v40, v11
	s_waitcnt lgkmcnt(2)
	v_add_f32_e32 v11, v24, v12
	s_waitcnt lgkmcnt(1)
	v_add_f32_e32 v12, v16, v15
	v_xor_b32_e32 v15, 32, v204
	v_cmp_lt_i32_e32 vcc, v15, v13
	s_waitcnt lgkmcnt(0)
	v_add_f32_e32 v14, v14, v17
	v_cvt_pk_bf16_f32 v152, v150, v151
	v_cvt_pk_bf16_f32 v154, v156, v157
	global_store_dwordx4 v[142:143], v[152:155], off offset:256
	v_cndmask_b32_e32 v13, v204, v15, vcc
	v_lshlrev_b32_e32 v21, 2, v13
	ds_bpermute_b32 v13, v21, v4
	ds_bpermute_b32 v15, v21, v5
	ds_bpermute_b32 v16, v21, v8
	ds_bpermute_b32 v17, v21, v9
	ds_bpermute_b32 v18, v21, v10
	ds_bpermute_b32 v19, v21, v11
	ds_bpermute_b32 v20, v21, v12
	ds_bpermute_b32 v21, v21, v14
	v_cvt_pk_bf16_f32 v126, v122, v123
	global_store_dwordx4 v[140:141], v[124:127], off
	v_cvt_pk_bf16_f32 v116, v112, v113
	global_store_dwordx4 v[140:141], v[114:117], off offset:256
	v_cvt_pk_bf16_f32 v23, v6, v7
	v_cvt_pk_bf16_f32 v24, v0, v1
	v_cvt_pk_bf16_f32 v25, v2, v3
	global_store_dwordx4 v[96:97], v[22:25], off offset:256
	s_and_saveexec_b64 s[0:1], s[2:3]
	s_mov_b32 s53, 0x28000
	s_mov_b32 s58, 0x34000
	s_mov_b32 s59, 0x38000
	s_mov_b32 s60, 0x3c000
	s_mov_b32 s61, 0x44000
	s_mov_b32 s62, 0x48000
	s_cbranch_execz .LBB0_239
	s_waitcnt lgkmcnt(7)
	v_add_f32_e32 v4, v4, v13
	s_waitcnt lgkmcnt(6)
	v_add_f32_e32 v5, v5, v15
	v_fma_f32 v4, v4, s67, 0.5
	s_waitcnt lgkmcnt(5)
	v_add_f32_e32 v8, v8, v16
	v_cvt_u32_f32_e32 v4, v4
	v_fma_f32 v5, v5, s67, 0.5
	s_waitcnt lgkmcnt(4)
	v_add_f32_e32 v9, v9, v17
	v_cvt_u32_f32_e32 v5, v5
	v_fma_f32 v8, v8, s67, 0.5
	v_cvt_u32_f32_e32 v8, v8
	v_fma_f32 v9, v9, s67, 0.5
	s_waitcnt lgkmcnt(3)
	v_add_f32_e32 v7, v10, v18
	v_lshl_add_u64 v[0:1], v[138:139], 2, s[8:9]
	v_cvt_u32_f32_e32 v9, v9
	s_waitcnt lgkmcnt(2)
	v_add_f32_e32 v6, v11, v19
	global_atomic_add v[0:1], v4, off
	global_atomic_add v[0:1], v5, off offset:64
	global_atomic_add v[0:1], v8, off offset:128
	global_atomic_add v[0:1], v9, off offset:192
	v_fma_f32 v4, v7, s67, 0.5
	s_waitcnt lgkmcnt(1)
	v_add_f32_e32 v3, v12, v20
	v_cvt_u32_f32_e32 v4, v4
	v_fma_f32 v5, v6, s67, 0.5
	s_waitcnt lgkmcnt(0)
	v_add_f32_e32 v2, v14, v21
	v_cvt_u32_f32_e32 v5, v5
	v_fma_f32 v3, v3, s67, 0.5
	v_cvt_u32_f32_e32 v3, v3
	v_fma_f32 v2, v2, s67, 0.5
	v_cvt_u32_f32_e32 v2, v2
	global_atomic_add v[0:1], v4, off offset:512
	global_atomic_add v[0:1], v5, off offset:576
	global_atomic_add v[0:1], v3, off offset:640
	global_atomic_add v[0:1], v2, off offset:704

; #define ER_LOAD(ai) _Pragma("unroll") for (int m = 0; m < 4; ++m) _Pragma("unroll") for (int bj = 0; bj < 2; ++bj) xv[m][bj] = *(const u32x4*)(x16 + base + (size_t)((ai) * HALF + m * 16) * D + bj * HALF);
; #define ER_ADD(ai) _Pragma("unroll") for (int m = 0; m < 4; ++m) _Pragma("unroll") for (int bj = 0; bj < 2; ++bj) { const u32x4 w = xv[m][bj]; \
;             acc[ai][bj][m][0] += (f32x4){h_lo(w.x), h_hi(w.x), h_lo(w.y), h_hi(w.y)}; acc[ai][bj][m][1] += (f32x4){h_lo(w.z), h_hi(w.z), h_lo(w.w), h_hi(w.w)}; }
;     __device__ __forceinline__ void operator()(Acc& acc, const Unit& u, int wr, int wc, int fr, int fq) const {
;     ...
;         ER_LOAD(0); ER_ADD(0); ER_LOAD(1); ER_STORE(0); ER_ADD(1); ER_STORE(1);
.LBB0_601:
	v_lshl_add_u32 v138, s1, 8, v162
	v_ashrrev_i32_e32 v139, 31, v138
	v_lshl_or_b32 v140, s0, 8, v164
	v_lshlrev_b64 v[142:143], 12, v[138:139]
	v_ashrrev_i32_e32 v141, 31, v140
	v_lshl_add_u64 v[142:143], s[10:11], 0, v[142:143]
	v_lshl_add_u64 v[146:147], v[140:141], 1, v[142:143]
	v_add_co_u32_e32 v144, vcc, 0x10000, v146
	global_load_dwordx4 v[148:151], v[146:147], off
	global_load_dwordx4 v[152:155], v[146:147], off offset:256
	v_addc_co_u32_e32 v145, vcc, 0, v147, vcc
	global_load_dwordx4 v[156:159], v[144:145], off
	global_load_dwordx4 v[166:169], v[144:145], off offset:256
	v_add_co_u32_e32 v142, vcc, 0x20000, v146
	s_nop 1
	v_addc_co_u32_e32 v143, vcc, 0, v147, vcc
	global_load_dwordx4 v[170:173], v[142:143], off
	global_load_dwordx4 v[178:181], v[142:143], off offset:256
	v_add_co_u32_e32 v140, vcc, 0x30000, v146
	s_nop 1
	v_addc_co_u32_e32 v141, vcc, 0, v147, vcc
	global_load_dwordx4 v[182:185], v[140:141], off
	global_load_dwordx4 v[186:189], v[140:141], off offset:256
	s_waitcnt vmcnt(4)
	v_lshlrev_b32_e32 v174, 16, v150
	v_and_b32_e32 v175, 0xffff0000, v150
	v_lshlrev_b32_e32 v150, 16, v151
	v_and_b32_e32 v151, 0xffff0000, v151
	v_lshlrev_b32_e32 v160, 16, v148
	v_and_b32_e32 v161, 0xffff0000, v148
	v_lshlrev_b32_e32 v148, 16, v149
	v_and_b32_e32 v149, 0xffff0000, v149
	v_lshlrev_b32_e32 v190, 16, v152
	v_and_b32_e32 v191, 0xffff0000, v152
	v_lshlrev_b32_e32 v152, 16, v153
	v_and_b32_e32 v153, 0xffff0000, v153
	v_pk_add_f32 v[200:201], v[122:123], v[150:151]
	v_lshlrev_b32_e32 v122, 16, v167
	v_and_b32_e32 v123, 0xffff0000, v167
	v_lshlrev_b32_e32 v192, 16, v154
	v_and_b32_e32 v193, 0xffff0000, v154
	v_lshlrev_b32_e32 v154, 16, v155
	v_and_b32_e32 v155, 0xffff0000, v155
	v_pk_add_f32 v[194:195], v[126:127], v[148:149]
	v_pk_add_f32 v[198:199], v[124:125], v[160:161]
	v_pk_add_f32 v[208:209], v[118:119], v[152:153]
	v_pk_add_f32 v[190:191], v[116:117], v[190:191]
	v_lshlrev_b32_e32 v116, 16, v158
	v_and_b32_e32 v117, 0xffff0000, v158
	v_lshlrev_b32_e32 v118, 16, v159
	v_and_b32_e32 v119, 0xffff0000, v159
	v_lshlrev_b32_e32 v124, 16, v168
	v_and_b32_e32 v125, 0xffff0000, v168
	v_lshlrev_b32_e32 v126, 16, v169
	v_and_b32_e32 v127, 0xffff0000, v169
	v_pk_add_f32 v[158:159], v[102:103], v[122:123]
	v_pk_add_f32 v[174:175], v[120:121], v[174:175]
	v_pk_add_f32 v[210:211], v[114:115], v[154:155]
	v_lshlrev_b32_e32 v120, 16, v166
	v_and_b32_e32 v121, 0xffff0000, v166
	v_pk_add_f32 v[216:217], v[106:107], v[118:119]
	v_pk_add_f32 v[154:155], v[90:91], v[126:127]
	v_pk_add_f32 v[220:221], v[88:89], v[124:125]
	v_pk_add_f32 v[160:161], v[100:101], v[120:121]
	v_pk_add_f32 v[192:193], v[112:113], v[192:193]
	v_lshlrev_b32_e32 v112, 16, v156
	v_and_b32_e32 v113, 0xffff0000, v156
	v_lshlrev_b32_e32 v114, 16, v157
	v_and_b32_e32 v115, 0xffff0000, v157
	v_pk_add_f32 v[212:213], v[110:111], v[114:115]
	v_pk_add_f32 v[218:219], v[104:105], v[116:117]
	v_pk_add_f32 v[214:215], v[108:109], v[112:113]
	v_cvt_pk_bf16_f32 v166, v198, v199
	v_cvt_pk_bf16_f32 v167, v194, v195
	v_cvt_pk_bf16_f32 v168, v174, v175
	v_cvt_pk_bf16_f32 v169, v200, v201
	s_waitcnt vmcnt(3)
	v_lshlrev_b32_e32 v102, 16, v173
	v_and_b32_e32 v103, 0xffff0000, v173
	v_lshlrev_b32_e32 v88, 16, v170
	v_and_b32_e32 v89, 0xffff0000, v170
	v_lshlrev_b32_e32 v90, 16, v171
	v_and_b32_e32 v91, 0xffff0000, v171
	v_pk_add_f32 v[118:119], v[94:95], v[102:103]
	v_add_co_u32_e32 v102, vcc, s77, v146
	v_lshlrev_b32_e32 v100, 16, v172
	v_and_b32_e32 v101, 0xffff0000, v172
	v_pk_add_f32 v[148:149], v[98:99], v[90:91]
	v_pk_add_f32 v[152:153], v[96:97], v[88:89]
	s_waitcnt vmcnt(2)
	v_lshlrev_b32_e32 v88, 16, v178
	v_and_b32_e32 v89, 0xffff0000, v178
	v_lshlrev_b32_e32 v90, 16, v179
	v_and_b32_e32 v91, 0xffff0000, v179
	v_addc_co_u32_e32 v103, vcc, 0, v147, vcc
	v_pk_add_f32 v[126:127], v[92:93], v[100:101]
	v_pk_add_f32 v[120:121], v[82:83], v[90:91]
	v_pk_add_f32 v[150:151], v[80:81], v[88:89]
	global_load_dwordx4 v[92:95], v[102:103], off
	global_load_dwordx4 v[88:91], v[102:103], off offset:256
	v_lshlrev_b32_e32 v80, 16, v180
	v_and_b32_e32 v81, 0xffff0000, v180
	v_lshlrev_b32_e32 v82, 16, v181
	v_and_b32_e32 v83, 0xffff0000, v181
	v_add_co_u32_e32 v100, vcc, s76, v146
	v_pk_add_f32 v[124:125], v[74:75], v[82:83]
	v_pk_add_f32 v[156:157], v[72:73], v[80:81]
	s_waitcnt vmcnt(3)
	v_lshlrev_b32_e32 v72, 16, v182
	v_and_b32_e32 v73, 0xffff0000, v182
	v_lshlrev_b32_e32 v74, 16, v183
	v_and_b32_e32 v75, 0xffff0000, v183
	v_addc_co_u32_e32 v101, vcc, 0, v147, vcc
	v_pk_add_f32 v[110:111], v[86:87], v[74:75]
	v_pk_add_f32 v[116:117], v[84:85], v[72:73]
	global_load_dwordx4 v[84:87], v[100:101], off
	global_load_dwordx4 v[80:83], v[100:101], off offset:256
	v_lshlrev_b32_e32 v72, 16, v184
	v_and_b32_e32 v73, 0xffff0000, v184
	v_lshlrev_b32_e32 v74, 16, v185
	v_and_b32_e32 v75, 0xffff0000, v185
	v_add_co_u32_e32 v98, vcc, s56, v146
	v_pk_add_f32 v[114:115], v[78:79], v[74:75]
	v_pk_add_f32 v[122:123], v[76:77], v[72:73]
	s_waitcnt vmcnt(4)
; #define ER_LOAD(ai) _Pragma("unroll") for (int m = 0; m < 4; ++m) _Pragma("unroll") for (int bj = 0; bj < 2; ++bj) xv[m][bj] = *(const u32x4*)(x16 + base + (size_t)((ai) * HALF + m * 16) * D + bj * HALF);
; #define ER_ADD(ai) _Pragma("unroll") for (int m = 0; m < 4; ++m) _Pragma("unroll") for (int bj = 0; bj < 2; ++bj) { const u32x4 w = xv[m][bj]; \
;             acc[ai][bj][m][0] += (f32x4){h_lo(w.x), h_hi(w.x), h_lo(w.y), h_hi(w.y)}; acc[ai][bj][m][1] += (f32x4){h_lo(w.z), h_hi(w.z), h_lo(w.w), h_hi(w.w)}; }
;     __device__ __forceinline__ void operator()(Acc& acc, const Unit& u, int wr, int wc, int fr, int fq) const {
;     ...
;         ER_LOAD(0); ER_ADD(0); ER_LOAD(1); ER_STORE(0); ER_ADD(1); ER_STORE(1);
	v_lshlrev_b32_e32 v72, 16, v186
	v_and_b32_e32 v73, 0xffff0000, v186
	v_lshlrev_b32_e32 v74, 16, v187
	v_and_b32_e32 v75, 0xffff0000, v187
	v_addc_co_u32_e32 v99, vcc, 0, v147, vcc
	v_pk_add_f32 v[104:105], v[70:71], v[74:75]
	v_pk_add_f32 v[108:109], v[68:69], v[72:73]
	global_load_dwordx4 v[76:79], v[98:99], off
	global_load_dwordx4 v[72:75], v[98:99], off offset:256
	v_add_co_u32_e32 v96, vcc, s68, v146
	v_lshlrev_b32_e32 v68, 16, v188
	v_and_b32_e32 v69, 0xffff0000, v188
	v_lshlrev_b32_e32 v70, 16, v189
	v_and_b32_e32 v71, 0xffff0000, v189
	v_addc_co_u32_e32 v97, vcc, 0, v147, vcc
	v_pk_add_f32 v[106:107], v[66:67], v[70:71]
	v_pk_add_f32 v[112:113], v[64:65], v[68:69]
	global_load_dwordx4 v[68:71], v[96:97], off
	global_load_dwordx4 v[64:67], v[96:97], off offset:256
	s_nop 0
	global_store_dwordx4 v[146:147], v[166:169], off
	s_nop 1
	v_mul_f32_e32 v166, v199, v199
	v_mul_f32_e32 v167, v195, v195
	v_fmac_f32_e32 v166, v198, v198
	v_fmac_f32_e32 v167, v194, v194
	v_add_f32_e32 v166, v166, v167
	v_mul_f32_e32 v167, v175, v175
	v_fmac_f32_e32 v167, v174, v174
	v_add_f32_e32 v166, v167, v166
	v_mul_f32_e32 v167, v201, v201
	v_fmac_f32_e32 v167, v200, v200
	v_add_f32_e32 v170, v167, v166
	v_cvt_pk_bf16_f32 v166, v190, v191
	v_cvt_pk_bf16_f32 v167, v208, v209
	v_cvt_pk_bf16_f32 v168, v192, v193
	v_cvt_pk_bf16_f32 v169, v210, v211
	global_store_dwordx4 v[146:147], v[166:169], off offset:256
	v_mul_f32_e32 v146, v191, v191
	v_mul_f32_e32 v147, v209, v209
	v_fmac_f32_e32 v146, v190, v190
	v_fmac_f32_e32 v147, v208, v208
	v_add_f32_e32 v146, v146, v147
	v_mul_f32_e32 v147, v193, v193
	v_fmac_f32_e32 v147, v192, v192
	v_add_f32_e32 v146, v147, v146
	v_mul_f32_e32 v147, v211, v211
	v_fmac_f32_e32 v147, v210, v210
	v_cvt_pk_bf16_f32 v166, v214, v215
	v_add_f32_e32 v146, v147, v146
	v_cvt_pk_bf16_f32 v167, v212, v213
	v_cvt_pk_bf16_f32 v168, v218, v219
	v_cvt_pk_bf16_f32 v169, v216, v217
	global_store_dwordx4 v[144:145], v[166:169], off
	v_mul_f32_e32 v147, v215, v215
	v_fmac_f32_e32 v147, v214, v214
	v_mul_f32_e32 v166, v213, v213
	v_fmac_f32_e32 v166, v212, v212
	v_add_f32_e32 v147, v147, v166
	v_mul_f32_e32 v166, v219, v219
	v_fmac_f32_e32 v166, v218, v218
	v_add_f32_e32 v147, v166, v147
	v_mul_f32_e32 v166, v217, v217
	v_fmac_f32_e32 v166, v216, v216
	v_add_f32_e32 v147, v166, v147
	v_cvt_pk_bf16_f32 v166, v160, v161
	v_cvt_pk_bf16_f32 v167, v158, v159
	v_cvt_pk_bf16_f32 v168, v220, v221
	v_cvt_pk_bf16_f32 v169, v154, v155
	global_store_dwordx4 v[144:145], v[166:169], off offset:256
	v_mul_f32_e32 v144, v161, v161
	v_mul_f32_e32 v145, v159, v159
	v_fmac_f32_e32 v144, v160, v160
	v_fmac_f32_e32 v145, v158, v158
	v_add_f32_e32 v144, v144, v145
	v_mul_f32_e32 v145, v221, v221
	v_fmac_f32_e32 v145, v220, v220
	v_add_f32_e32 v144, v145, v144
	v_mul_f32_e32 v145, v155, v155
	v_fmac_f32_e32 v145, v154, v154
	v_add_f32_e32 v144, v145, v144
	v_add_f32_e32 v144, v147, v144
	v_mul_f32_e32 v145, v153, v153
	v_mul_f32_e32 v147, v149, v149
	v_cvt_pk_bf16_f32 v160, v126, v127
	v_fmac_f32_e32 v145, v152, v152
	v_fmac_f32_e32 v147, v148, v148
	v_mul_f32_e32 v127, v127, v127
	v_cvt_pk_bf16_f32 v161, v118, v119
	v_add_f32_e32 v145, v145, v147
	v_fmac_f32_e32 v127, v126, v126
	v_mul_f32_e32 v119, v119, v119
	v_add_f32_e32 v126, v127, v145
	v_fmac_f32_e32 v119, v118, v118
	v_cvt_pk_bf16_f32 v158, v152, v153
	v_add_f32_e32 v118, v119, v126
	v_cvt_pk_bf16_f32 v153, v120, v121
	v_mul_f32_e32 v119, v151, v151
	v_mul_f32_e32 v121, v121, v121
	v_fmac_f32_e32 v119, v150, v150
	v_fmac_f32_e32 v121, v120, v120
	v_mul_f32_e32 v120, v157, v157
	v_add_f32_e32 v119, v119, v121
	v_fmac_f32_e32 v120, v156, v156
	v_add_f32_e32 v119, v120, v119
	v_mul_f32_e32 v120, v125, v125
	v_cvt_pk_bf16_f32 v155, v124, v125
	v_fmac_f32_e32 v120, v124, v124
	v_cvt_pk_bf16_f32 v124, v116, v117
	v_cvt_pk_bf16_f32 v125, v110, v111
	v_mul_f32_e32 v117, v117, v117
	v_mul_f32_e32 v111, v111, v111
	v_fmac_f32_e32 v117, v116, v116
	v_fmac_f32_e32 v111, v110, v110
	v_add_f32_e32 v110, v117, v111
	v_mul_f32_e32 v111, v123, v123
	v_fmac_f32_e32 v111, v122, v122
	v_add_f32_e32 v110, v111, v110
	v_mul_f32_e32 v111, v115, v115
	v_cvt_pk_bf16_f32 v127, v114, v115
	v_fmac_f32_e32 v111, v114, v114
	v_cvt_pk_bf16_f32 v114, v108, v109
	v_cvt_pk_bf16_f32 v115, v104, v105
	v_mul_f32_e32 v109, v109, v109
	v_mul_f32_e32 v105, v105, v105
	v_fmac_f32_e32 v109, v108, v108
	v_fmac_f32_e32 v105, v104, v104
	v_add_f32_e32 v104, v109, v105
	v_mul_f32_e32 v105, v113, v113
	v_fmac_f32_e32 v105, v112, v112
	v_add_f32_e32 v104, v105, v104
	v_mul_f32_e32 v105, v107, v107
	v_fmac_f32_e32 v105, v106, v106
	v_add_f32_e32 v110, v111, v110
	v_add_f32_e32 v104, v105, v104
	v_cvt_pk_bf16_f32 v117, v106, v107
	v_add_f32_e32 v106, v110, v104
	s_waitcnt vmcnt(11)
	v_lshlrev_b32_e32 v104, 16, v92
	v_and_b32_e32 v105, 0xffff0000, v92
	v_lshlrev_b32_e32 v92, 16, v93
	v_and_b32_e32 v93, 0xffff0000, v93
	v_pk_add_f32 v[62:63], v[62:63], v[92:93]
	v_lshlrev_b32_e32 v92, 16, v94
	v_and_b32_e32 v93, 0xffff0000, v94
	v_pk_add_f32 v[56:57], v[56:57], v[92:93]
	s_waitcnt vmcnt(10)
	v_lshlrev_b32_e32 v92, 16, v88
	v_and_b32_e32 v93, 0xffff0000, v88
	v_lshlrev_b32_e32 v88, 16, v89
	v_and_b32_e32 v89, 0xffff0000, v89
	v_pk_add_f32 v[50:51], v[50:51], v[88:89]
	v_lshlrev_b32_e32 v88, 16, v90
	v_and_b32_e32 v89, 0xffff0000, v90
	v_pk_add_f32 v[40:41], v[40:41], v[88:89]
	s_waitcnt vmcnt(9)
	v_lshlrev_b32_e32 v88, 16, v84
	v_and_b32_e32 v89, 0xffff0000, v84
	v_lshlrev_b32_e32 v84, 16, v85
	v_and_b32_e32 v85, 0xffff0000, v85
	v_pk_add_f32 v[54:55], v[54:55], v[84:85]
	v_lshlrev_b32_e32 v84, 16, v86
	v_and_b32_e32 v85, 0xffff0000, v86
	v_pk_add_f32 v[44:45], v[44:45], v[84:85]
	s_waitcnt vmcnt(8)
; #define ER_LOAD(ai) _Pragma("unroll") for (int m = 0; m < 4; ++m) _Pragma("unroll") for (int bj = 0; bj < 2; ++bj) xv[m][bj] = *(const u32x4*)(x16 + base + (size_t)((ai) * HALF + m * 16) * D + bj * HALF);
; #define ER_ADD(ai) _Pragma("unroll") for (int m = 0; m < 4; ++m) _Pragma("unroll") for (int bj = 0; bj < 2; ++bj) { const u32x4 w = xv[m][bj]; \
;             acc[ai][bj][m][0] += (f32x4){h_lo(w.x), h_hi(w.x), h_lo(w.y), h_hi(w.y)}; acc[ai][bj][m][1] += (f32x4){h_lo(w.z), h_hi(w.z), h_lo(w.w), h_hi(w.w)}; }
;     __device__ __forceinline__ void operator()(Acc& acc, const Unit& u, int wr, int wc, int fr, int fq) const {
;     ...
;         ER_LOAD(0); ER_ADD(0); ER_LOAD(1); ER_STORE(0); ER_ADD(1); ER_STORE(1);
	v_lshlrev_b32_e32 v84, 16, v80
	v_and_b32_e32 v85, 0xffff0000, v80
	v_lshlrev_b32_e32 v80, 16, v81
	v_and_b32_e32 v81, 0xffff0000, v81
	v_pk_add_f32 v[34:35], v[34:35], v[80:81]
	v_lshlrev_b32_e32 v80, 16, v82
	v_and_b32_e32 v81, 0xffff0000, v82
	v_pk_add_f32 v[24:25], v[24:25], v[80:81]
	s_waitcnt vmcnt(7)
	v_lshlrev_b32_e32 v80, 16, v76
	v_and_b32_e32 v81, 0xffff0000, v76
	v_lshlrev_b32_e32 v76, 16, v77
	v_and_b32_e32 v77, 0xffff0000, v77
	v_pk_add_f32 v[38:39], v[38:39], v[76:77]
	v_lshlrev_b32_e32 v76, 16, v78
	v_and_b32_e32 v77, 0xffff0000, v78
	v_pk_add_f32 v[28:29], v[28:29], v[76:77]
	s_waitcnt vmcnt(6)
	v_lshlrev_b32_e32 v76, 16, v72
	v_and_b32_e32 v77, 0xffff0000, v72
	v_lshlrev_b32_e32 v72, 16, v73
	v_and_b32_e32 v73, 0xffff0000, v73
	v_pk_add_f32 v[18:19], v[18:19], v[72:73]
	v_lshlrev_b32_e32 v72, 16, v74
	v_and_b32_e32 v73, 0xffff0000, v74
	v_lshlrev_b32_e32 v74, 16, v75
	v_and_b32_e32 v75, 0xffff0000, v75
	v_pk_add_f32 v[74:75], v[10:11], v[74:75]
	v_pk_add_f32 v[72:73], v[8:9], v[72:73]
	s_waitcnt vmcnt(5)
	v_lshlrev_b32_e32 v10, 16, v68
	v_and_b32_e32 v11, 0xffff0000, v68
	v_lshlrev_b32_e32 v8, 16, v69
	v_and_b32_e32 v9, 0xffff0000, v69
	v_pk_add_f32 v[8:9], v[22:23], v[8:9]
	v_pk_add_f32 v[20:21], v[20:21], v[10:11]
	v_lshlrev_b32_e32 v10, 16, v70
	v_and_b32_e32 v11, 0xffff0000, v70
	v_lshlrev_b32_e32 v22, 16, v71
	v_and_b32_e32 v23, 0xffff0000, v71
	v_pk_add_f32 v[14:15], v[14:15], v[22:23]
	v_pk_add_f32 v[22:23], v[12:13], v[10:11]
	s_waitcnt vmcnt(4)
	v_lshlrev_b32_e32 v10, 16, v64
	v_and_b32_e32 v11, 0xffff0000, v64
	v_lshlrev_b32_e32 v12, 16, v65
	v_and_b32_e32 v13, 0xffff0000, v65
	v_pk_add_f32 v[4:5], v[4:5], v[10:11]
	v_lshlrev_b32_e32 v10, 16, v66
	v_and_b32_e32 v11, 0xffff0000, v66
	v_pk_add_f32 v[60:61], v[60:61], v[104:105]
	v_lshlrev_b32_e32 v94, 16, v95
	v_and_b32_e32 v95, 0xffff0000, v95
	v_pk_add_f32 v[6:7], v[6:7], v[12:13]
	v_lshlrev_b32_e32 v12, 16, v67
	v_and_b32_e32 v13, 0xffff0000, v67
	v_pk_add_f32 v[0:1], v[0:1], v[10:11]
	v_cvt_pk_bf16_f32 v10, v60, v61
	v_cvt_pk_bf16_f32 v11, v62, v63
	v_pk_add_f32 v[58:59], v[58:59], v[94:95]
	v_pk_add_f32 v[2:3], v[2:3], v[12:13]
	v_cvt_pk_bf16_f32 v12, v56, v57
	v_cvt_pk_bf16_f32 v13, v58, v59
	global_store_dwordx4 v[102:103], v[10:13], off
	v_pk_add_f32 v[48:49], v[48:49], v[92:93]
	v_lshlrev_b32_e32 v90, 16, v91
	v_mul_f32_e32 v10, v61, v61
	v_mul_f32_e32 v11, v63, v63
	v_fmac_f32_e32 v10, v60, v60
	v_fmac_f32_e32 v11, v62, v62
	v_add_f32_e32 v10, v10, v11
	v_mul_f32_e32 v11, v57, v57
	v_fmac_f32_e32 v11, v56, v56
	v_add_f32_e32 v10, v11, v10
	v_mul_f32_e32 v11, v59, v59
	v_fmac_f32_e32 v11, v58, v58
	v_and_b32_e32 v91, 0xffff0000, v91
	v_add_f32_e32 v56, v11, v10
	v_cvt_pk_bf16_f32 v10, v48, v49
	v_cvt_pk_bf16_f32 v11, v50, v51
	v_pk_add_f32 v[42:43], v[42:43], v[90:91]
	v_cvt_pk_bf16_f32 v12, v40, v41
	v_pk_add_f32 v[52:53], v[52:53], v[88:89]
	v_cvt_pk_bf16_f32 v13, v42, v43
	global_store_dwordx4 v[102:103], v[10:13], off offset:256
	v_lshlrev_b32_e32 v86, 16, v87
	v_and_b32_e32 v87, 0xffff0000, v87
	v_mul_f32_e32 v10, v49, v49
	v_mul_f32_e32 v11, v51, v51
	v_fmac_f32_e32 v10, v48, v48
	v_fmac_f32_e32 v11, v50, v50
	v_add_f32_e32 v10, v10, v11
	v_mul_f32_e32 v11, v41, v41
	v_fmac_f32_e32 v11, v40, v40
	v_add_f32_e32 v10, v11, v10
	v_mul_f32_e32 v11, v43, v43
	v_fmac_f32_e32 v11, v42, v42
	v_add_f32_e32 v10, v11, v10
	v_add_f32_e32 v40, v56, v10
	v_cvt_pk_bf16_f32 v10, v52, v53
	v_cvt_pk_bf16_f32 v11, v54, v55
	v_pk_add_f32 v[46:47], v[46:47], v[86:87]
	v_cvt_pk_bf16_f32 v12, v44, v45
	v_pk_add_f32 v[32:33], v[32:33], v[84:85]
	v_cvt_pk_bf16_f32 v13, v46, v47
	global_store_dwordx4 v[100:101], v[10:13], off
	v_lshlrev_b32_e32 v82, 16, v83
	v_and_b32_e32 v83, 0xffff0000, v83
	v_mul_f32_e32 v10, v53, v53
	v_mul_f32_e32 v11, v55, v55
	v_fmac_f32_e32 v10, v52, v52
	v_fmac_f32_e32 v11, v54, v54
	v_add_f32_e32 v10, v10, v11
	v_mul_f32_e32 v11, v45, v45
	v_fmac_f32_e32 v11, v44, v44
	v_add_f32_e32 v10, v11, v10
	v_mul_f32_e32 v11, v47, v47
	v_fmac_f32_e32 v11, v46, v46
	v_add_f32_e32 v41, v11, v10
	v_cvt_pk_bf16_f32 v10, v32, v33
	v_cvt_pk_bf16_f32 v11, v34, v35
	v_pk_add_f32 v[26:27], v[26:27], v[82:83]
	v_cvt_pk_bf16_f32 v12, v24, v25
	v_pk_add_f32 v[36:37], v[36:37], v[80:81]
	v_cvt_pk_bf16_f32 v13, v26, v27
	global_store_dwordx4 v[100:101], v[10:13], off offset:256
	v_lshlrev_b32_e32 v78, 16, v79
	v_and_b32_e32 v79, 0xffff0000, v79
	v_mul_f32_e32 v10, v33, v33
	v_mul_f32_e32 v11, v35, v35
	v_fmac_f32_e32 v10, v32, v32
	v_fmac_f32_e32 v11, v34, v34
	v_add_f32_e32 v10, v10, v11
	v_mul_f32_e32 v11, v25, v25
	v_fmac_f32_e32 v11, v24, v24
	v_add_f32_e32 v10, v11, v10
	v_mul_f32_e32 v11, v27, v27
	v_fmac_f32_e32 v11, v26, v26
	v_add_f32_e32 v10, v11, v10
	v_add_f32_e32 v24, v41, v10
	v_cvt_pk_bf16_f32 v10, v36, v37
	v_cvt_pk_bf16_f32 v11, v38, v39
	v_pk_add_f32 v[30:31], v[30:31], v[78:79]
	v_cvt_pk_bf16_f32 v12, v28, v29
	v_pk_add_f32 v[16:17], v[16:17], v[76:77]
	v_cvt_pk_bf16_f32 v13, v30, v31
; __device__ __forceinline__ void ssq_add(ssq_t* p, float v) { __hip_atomic_fetch_add(p, ssq_fix(v), __ATOMIC_RELAXED, __HIP_MEMORY_SCOPE_AGENT); }
; #define ER_LOAD(ai) _Pragma("unroll") for (int m = 0; m < 4; ++m) _Pragma("unroll") for (int bj = 0; bj < 2; ++bj) xv[m][bj] = *(const u32x4*)(x16 + base + (size_t)((ai) * HALF + m * 16) * D + bj * HALF);
; #define ER_ADD(ai) _Pragma("unroll") for (int m = 0; m < 4; ++m) _Pragma("unroll") for (int bj = 0; bj < 2; ++bj) { const u32x4 w = xv[m][bj]; \
;             acc[ai][bj][m][0] += (f32x4){h_lo(w.x), h_hi(w.x), h_lo(w.y), h_hi(w.y)}; acc[ai][bj][m][1] += (f32x4){h_lo(w.z), h_hi(w.z), h_lo(w.w), h_hi(w.w)}; }
;     __device__ __forceinline__ void operator()(Acc& acc, const Unit& u, int wr, int wc, int fr, int fq) const {
;     ...
;         ER_LOAD(0); ER_ADD(0); ER_LOAD(1); ER_STORE(0); ER_ADD(1); ER_STORE(1);
;     ...
; #pragma unroll
;         for (int q = 0; q < 8; ++q) { ssv[q] += __shfl_xor(ssv[q], 16); }
; #pragma unroll
;         for (int q = 0; q < 8; ++q) { ssv[q] += __shfl_xor(ssv[q], 32); }
;         if (fq == 0) {
; #pragma unroll
;             for (int q = 0; q < 8; ++q) ssq_add(ssq_out + row0 + (q >> 2) * HALF + (q & 3) * 16, ssv[q]);
	global_store_dwordx4 v[98:99], v[10:13], off
	v_add_f32_e32 v119, v120, v119
	v_add_f32_e32 v146, v170, v146
	v_mul_f32_e32 v10, v37, v37
	v_mul_f32_e32 v11, v39, v39
	v_fmac_f32_e32 v10, v36, v36
	v_fmac_f32_e32 v11, v38, v38
	v_add_f32_e32 v10, v10, v11
	v_mul_f32_e32 v11, v29, v29
	v_fmac_f32_e32 v11, v28, v28
	v_add_f32_e32 v10, v11, v10
	v_mul_f32_e32 v11, v31, v31
	v_fmac_f32_e32 v11, v30, v30
	v_add_f32_e32 v25, v11, v10
	v_cvt_pk_bf16_f32 v10, v16, v17
	v_cvt_pk_bf16_f32 v11, v18, v19
	v_cvt_pk_bf16_f32 v12, v72, v73
	v_cvt_pk_bf16_f32 v13, v74, v75
	global_store_dwordx4 v[98:99], v[10:13], off offset:256
	v_add_f32_e32 v118, v118, v119
	v_cvt_pk_bf16_f32 v159, v148, v149
	global_store_dwordx4 v[142:143], v[158:161], off
	v_mul_f32_e32 v10, v17, v17
	v_mul_f32_e32 v11, v19, v19
	v_fmac_f32_e32 v10, v16, v16
	v_fmac_f32_e32 v11, v18, v18
	v_add_f32_e32 v10, v10, v11
	v_mul_f32_e32 v11, v73, v73
	v_fmac_f32_e32 v11, v72, v72
	v_add_f32_e32 v10, v11, v10
	v_mul_f32_e32 v11, v75, v75
	v_fmac_f32_e32 v11, v74, v74
	v_add_f32_e32 v10, v11, v10
	v_add_f32_e32 v16, v25, v10
	v_cvt_pk_bf16_f32 v10, v20, v21
	v_cvt_pk_bf16_f32 v11, v8, v9
	v_cvt_pk_bf16_f32 v12, v22, v23
	v_cvt_pk_bf16_f32 v13, v14, v15
	global_store_dwordx4 v[96:97], v[10:13], off
	v_mul_f32_e32 v9, v9, v9
	v_fmac_f32_e32 v9, v8, v8
	v_mul_f32_e32 v10, v21, v21
	v_fmac_f32_e32 v10, v20, v20
	v_add_f32_e32 v8, v10, v9
	v_mul_f32_e32 v9, v23, v23
	v_fmac_f32_e32 v9, v22, v22
	v_add_f32_e32 v8, v9, v8
	v_mul_f32_e32 v9, v15, v15
	v_fmac_f32_e32 v9, v14, v14
	v_and_b32_e32 v10, 64, v204
	v_add_f32_e32 v8, v9, v8
	v_xor_b32_e32 v9, 16, v204
	v_add_u32_e32 v13, 64, v10
	v_cvt_pk_bf16_f32 v22, v4, v5
	v_mul_f32_e32 v5, v5, v5
	v_cmp_lt_i32_e32 vcc, v9, v13
	v_fmac_f32_e32 v5, v4, v4
	v_mul_f32_e32 v4, v7, v7
	v_cndmask_b32_e32 v9, v204, v9, vcc
	v_fmac_f32_e32 v4, v6, v6
	v_lshlrev_b32_e32 v9, 2, v9
	v_add_f32_e32 v4, v5, v4
	v_mul_f32_e32 v5, v1, v1
	ds_bpermute_b32 v10, v9, v146
	ds_bpermute_b32 v11, v9, v144
	ds_bpermute_b32 v12, v9, v118
	v_fmac_f32_e32 v5, v0, v0
	v_add_f32_e32 v4, v5, v4
	v_mul_f32_e32 v5, v3, v3
	v_fmac_f32_e32 v5, v2, v2
	v_add_f32_e32 v4, v5, v4
	v_add_f32_e32 v14, v8, v4
	s_waitcnt lgkmcnt(2)
	v_add_f32_e32 v4, v146, v10
	s_waitcnt lgkmcnt(1)
	v_add_f32_e32 v5, v144, v11
	s_waitcnt lgkmcnt(0)
	v_add_f32_e32 v8, v118, v12
	ds_bpermute_b32 v10, v9, v106
	ds_bpermute_b32 v11, v9, v40
	ds_bpermute_b32 v12, v9, v24
	ds_bpermute_b32 v15, v9, v16
	ds_bpermute_b32 v17, v9, v14
	s_waitcnt lgkmcnt(4)
	v_add_f32_e32 v9, v106, v10
	s_waitcnt lgkmcnt(3)
	v_add_f32_e32 v10, v40, v11
	s_waitcnt lgkmcnt(2)
	v_add_f32_e32 v11, v24, v12
	s_waitcnt lgkmcnt(1)
	v_add_f32_e32 v12, v16, v15
	v_xor_b32_e32 v15, 32, v204
	v_cmp_lt_i32_e32 vcc, v15, v13
	s_waitcnt lgkmcnt(0)
	v_add_f32_e32 v14, v14, v17
	v_cvt_pk_bf16_f32 v152, v150, v151
	v_cvt_pk_bf16_f32 v154, v156, v157
	global_store_dwordx4 v[142:143], v[152:155], off offset:256
	v_cndmask_b32_e32 v13, v204, v15, vcc
	v_lshlrev_b32_e32 v21, 2, v13
	ds_bpermute_b32 v13, v21, v4
	ds_bpermute_b32 v15, v21, v5
	ds_bpermute_b32 v16, v21, v8
	ds_bpermute_b32 v17, v21, v9
	ds_bpermute_b32 v18, v21, v10
	ds_bpermute_b32 v19, v21, v11
	ds_bpermute_b32 v20, v21, v12
	ds_bpermute_b32 v21, v21, v14
	v_cvt_pk_bf16_f32 v126, v122, v123
	global_store_dwordx4 v[140:141], v[124:127], off
	v_cvt_pk_bf16_f32 v116, v112, v113
	global_store_dwordx4 v[140:141], v[114:117], off offset:256
	v_cvt_pk_bf16_f32 v23, v6, v7
	v_cvt_pk_bf16_f32 v24, v0, v1
	v_cvt_pk_bf16_f32 v25, v2, v3
	global_store_dwordx4 v[96:97], v[22:25], off offset:256
	s_and_saveexec_b64 s[0:1], s[2:3]
	s_mov_b32 s49, 0x60000
	s_mov_b32 s52, 0x24000
	s_mov_b32 s53, 0x28000
	s_mov_b32 s58, 0x34000
	s_mov_b32 s59, 0x38000
	s_cbranch_execz .LBB0_603
	s_waitcnt lgkmcnt(7)
	v_add_f32_e32 v4, v4, v13
	s_waitcnt lgkmcnt(6)
	v_add_f32_e32 v5, v5, v15
	v_fma_f32 v4, v4, s67, 0.5
	s_waitcnt lgkmcnt(5)
	v_add_f32_e32 v8, v8, v16
	v_cvt_u32_f32_e32 v4, v4
	v_fma_f32 v5, v5, s67, 0.5
	s_waitcnt lgkmcnt(4)
	v_add_f32_e32 v9, v9, v17
	v_cvt_u32_f32_e32 v5, v5
	v_fma_f32 v8, v8, s67, 0.5
	v_cvt_u32_f32_e32 v8, v8
	v_fma_f32 v9, v9, s67, 0.5
	s_waitcnt lgkmcnt(3)
	v_add_f32_e32 v7, v10, v18
	v_lshl_add_u64 v[0:1], v[138:139], 2, s[12:13]
	v_cvt_u32_f32_e32 v9, v9
	s_waitcnt lgkmcnt(2)
	v_add_f32_e32 v6, v11, v19
	global_atomic_add v[0:1], v4, off
	global_atomic_add v[0:1], v5, off offset:64
	global_atomic_add v[0:1], v8, off offset:128
	global_atomic_add v[0:1], v9, off offset:192
	v_fma_f32 v4, v7, s67, 0.5
	s_waitcnt lgkmcnt(1)
	v_add_f32_e32 v3, v12, v20
	v_cvt_u32_f32_e32 v4, v4
	v_fma_f32 v5, v6, s67, 0.5
	s_waitcnt lgkmcnt(0)
	v_add_f32_e32 v2, v14, v21
	v_cvt_u32_f32_e32 v5, v5
	v_fma_f32 v3, v3, s67, 0.5
	v_cvt_u32_f32_e32 v3, v3
	v_fma_f32 v2, v2, s67, 0.5
	v_cvt_u32_f32_e32 v2, v2
	global_atomic_add v[0:1], v4, off offset:512
	global_atomic_add v[0:1], v5, off offset:576
	global_atomic_add v[0:1], v3, off offset:640
	global_atomic_add v[0:1], v2, off offset:704

; #define ER_LOAD(ai) _Pragma("unroll") for (int m = 0; m < 4; ++m) _Pragma("unroll") for (int bj = 0; bj < 2; ++bj) xv[m][bj] = *(const u32x4*)(x16 + base + (size_t)((ai) * HALF + m * 16) * D + bj * HALF);
; #define ER_ADD(ai) _Pragma("unroll") for (int m = 0; m < 4; ++m) _Pragma("unroll") for (int bj = 0; bj < 2; ++bj) { const u32x4 w = xv[m][bj]; \
;             acc[ai][bj][m][0] += (f32x4){h_lo(w.x), h_hi(w.x), h_lo(w.y), h_hi(w.y)}; acc[ai][bj][m][1] += (f32x4){h_lo(w.z), h_hi(w.z), h_lo(w.w), h_hi(w.w)}; }
;     __device__ __forceinline__ void operator()(Acc& acc, const Unit& u, int wr, int wc, int fr, int fq) const {
;     ...
;         ER_LOAD(0); ER_ADD(0); ER_LOAD(1); ER_STORE(0); ER_ADD(1); ER_STORE(1);
.LBB0_798:
	v_lshl_add_u32 v138, s62, 8, v162
	v_ashrrev_i32_e32 v139, 31, v138
	v_lshl_or_b32 v140, s61, 8, v164
	v_lshlrev_b64 v[142:143], 12, v[138:139]
	v_ashrrev_i32_e32 v141, 31, v140
	v_lshl_add_u64 v[142:143], s[8:9], 0, v[142:143]
	v_lshl_add_u64 v[146:147], v[140:141], 1, v[142:143]
	v_add_co_u32_e32 v144, vcc, 0x10000, v146
	global_load_dwordx4 v[148:151], v[146:147], off
	global_load_dwordx4 v[152:155], v[146:147], off offset:256
	v_addc_co_u32_e32 v145, vcc, 0, v147, vcc
	global_load_dwordx4 v[156:159], v[144:145], off
	global_load_dwordx4 v[166:169], v[144:145], off offset:256
	v_add_co_u32_e32 v142, vcc, 0x20000, v146
	s_nop 1
	v_addc_co_u32_e32 v143, vcc, 0, v147, vcc
	global_load_dwordx4 v[170:173], v[142:143], off
	global_load_dwordx4 v[178:181], v[142:143], off offset:256
	v_add_co_u32_e32 v140, vcc, 0x30000, v146
	s_nop 1
	v_addc_co_u32_e32 v141, vcc, 0, v147, vcc
	global_load_dwordx4 v[182:185], v[140:141], off
	global_load_dwordx4 v[186:189], v[140:141], off offset:256
	s_waitcnt vmcnt(4)
	v_lshlrev_b32_e32 v174, 16, v150
	v_and_b32_e32 v175, 0xffff0000, v150
	v_lshlrev_b32_e32 v150, 16, v151
	v_and_b32_e32 v151, 0xffff0000, v151
	v_lshlrev_b32_e32 v160, 16, v148
	v_and_b32_e32 v161, 0xffff0000, v148
	v_lshlrev_b32_e32 v148, 16, v149
	v_and_b32_e32 v149, 0xffff0000, v149
	v_lshlrev_b32_e32 v190, 16, v152
	v_and_b32_e32 v191, 0xffff0000, v152
	v_lshlrev_b32_e32 v152, 16, v153
	v_and_b32_e32 v153, 0xffff0000, v153
	v_pk_add_f32 v[200:201], v[122:123], v[150:151]
	v_lshlrev_b32_e32 v122, 16, v167
	v_and_b32_e32 v123, 0xffff0000, v167
	v_lshlrev_b32_e32 v192, 16, v154
	v_and_b32_e32 v193, 0xffff0000, v154
	v_lshlrev_b32_e32 v154, 16, v155
	v_and_b32_e32 v155, 0xffff0000, v155
	v_pk_add_f32 v[194:195], v[126:127], v[148:149]
	v_pk_add_f32 v[198:199], v[124:125], v[160:161]
	v_pk_add_f32 v[202:203], v[118:119], v[152:153]
	v_pk_add_f32 v[190:191], v[116:117], v[190:191]
	v_lshlrev_b32_e32 v116, 16, v158
	v_and_b32_e32 v117, 0xffff0000, v158
	v_lshlrev_b32_e32 v118, 16, v159
	v_and_b32_e32 v119, 0xffff0000, v159
	v_lshlrev_b32_e32 v124, 16, v168
	v_and_b32_e32 v125, 0xffff0000, v168
	v_lshlrev_b32_e32 v126, 16, v169
	v_and_b32_e32 v127, 0xffff0000, v169
	v_pk_add_f32 v[158:159], v[102:103], v[122:123]
	v_pk_add_f32 v[174:175], v[120:121], v[174:175]
	v_pk_add_f32 v[208:209], v[114:115], v[154:155]
	v_lshlrev_b32_e32 v120, 16, v166
	v_and_b32_e32 v121, 0xffff0000, v166
	v_pk_add_f32 v[214:215], v[106:107], v[118:119]
	v_pk_add_f32 v[154:155], v[90:91], v[126:127]
	v_pk_add_f32 v[218:219], v[88:89], v[124:125]
	v_pk_add_f32 v[160:161], v[100:101], v[120:121]
	v_pk_add_f32 v[192:193], v[112:113], v[192:193]
	v_lshlrev_b32_e32 v112, 16, v156
	v_and_b32_e32 v113, 0xffff0000, v156
	v_lshlrev_b32_e32 v114, 16, v157
	v_and_b32_e32 v115, 0xffff0000, v157
	v_pk_add_f32 v[210:211], v[110:111], v[114:115]
	v_pk_add_f32 v[216:217], v[104:105], v[116:117]
	v_pk_add_f32 v[212:213], v[108:109], v[112:113]
	v_cvt_pk_bf16_f32 v166, v198, v199
	v_cvt_pk_bf16_f32 v167, v194, v195
	v_cvt_pk_bf16_f32 v168, v174, v175
	v_cvt_pk_bf16_f32 v169, v200, v201
	s_waitcnt vmcnt(3)
	v_lshlrev_b32_e32 v102, 16, v173
	v_and_b32_e32 v103, 0xffff0000, v173
	v_lshlrev_b32_e32 v88, 16, v170
	v_and_b32_e32 v89, 0xffff0000, v170
	v_lshlrev_b32_e32 v90, 16, v171
	v_and_b32_e32 v91, 0xffff0000, v171
	v_pk_add_f32 v[118:119], v[94:95], v[102:103]
	v_add_co_u32_e32 v102, vcc, s77, v146
	v_lshlrev_b32_e32 v100, 16, v172
	v_and_b32_e32 v101, 0xffff0000, v172
	v_pk_add_f32 v[148:149], v[98:99], v[90:91]
	v_pk_add_f32 v[152:153], v[96:97], v[88:89]
	s_waitcnt vmcnt(2)
	v_lshlrev_b32_e32 v88, 16, v178
	v_and_b32_e32 v89, 0xffff0000, v178
	v_lshlrev_b32_e32 v90, 16, v179
	v_and_b32_e32 v91, 0xffff0000, v179
	v_addc_co_u32_e32 v103, vcc, 0, v147, vcc
	v_pk_add_f32 v[126:127], v[92:93], v[100:101]
	v_pk_add_f32 v[120:121], v[82:83], v[90:91]
	v_pk_add_f32 v[150:151], v[80:81], v[88:89]
	global_load_dwordx4 v[92:95], v[102:103], off
	global_load_dwordx4 v[88:91], v[102:103], off offset:256
	v_lshlrev_b32_e32 v80, 16, v180
	v_and_b32_e32 v81, 0xffff0000, v180
	v_lshlrev_b32_e32 v82, 16, v181
	v_and_b32_e32 v83, 0xffff0000, v181
	v_add_co_u32_e32 v100, vcc, s76, v146
	v_pk_add_f32 v[124:125], v[74:75], v[82:83]
	v_pk_add_f32 v[156:157], v[72:73], v[80:81]
	s_waitcnt vmcnt(3)
	v_lshlrev_b32_e32 v72, 16, v182
	v_and_b32_e32 v73, 0xffff0000, v182
	v_lshlrev_b32_e32 v74, 16, v183
	v_and_b32_e32 v75, 0xffff0000, v183
	v_addc_co_u32_e32 v101, vcc, 0, v147, vcc
	v_pk_add_f32 v[110:111], v[86:87], v[74:75]
	v_pk_add_f32 v[116:117], v[84:85], v[72:73]
	global_load_dwordx4 v[84:87], v[100:101], off
	global_load_dwordx4 v[80:83], v[100:101], off offset:256
	v_lshlrev_b32_e32 v72, 16, v184
	v_and_b32_e32 v73, 0xffff0000, v184
	v_lshlrev_b32_e32 v74, 16, v185
	v_and_b32_e32 v75, 0xffff0000, v185
	v_add_co_u32_e32 v98, vcc, s56, v146
	v_pk_add_f32 v[114:115], v[78:79], v[74:75]
	v_pk_add_f32 v[122:123], v[76:77], v[72:73]
	s_waitcnt vmcnt(4)
; #define ER_LOAD(ai) _Pragma("unroll") for (int m = 0; m < 4; ++m) _Pragma("unroll") for (int bj = 0; bj < 2; ++bj) xv[m][bj] = *(const u32x4*)(x16 + base + (size_t)((ai) * HALF + m * 16) * D + bj * HALF);
; #define ER_ADD(ai) _Pragma("unroll") for (int m = 0; m < 4; ++m) _Pragma("unroll") for (int bj = 0; bj < 2; ++bj) { const u32x4 w = xv[m][bj]; \
;             acc[ai][bj][m][0] += (f32x4){h_lo(w.x), h_hi(w.x), h_lo(w.y), h_hi(w.y)}; acc[ai][bj][m][1] += (f32x4){h_lo(w.z), h_hi(w.z), h_lo(w.w), h_hi(w.w)}; }
;     __device__ __forceinline__ void operator()(Acc& acc, const Unit& u, int wr, int wc, int fr, int fq) const {
;     ...
;         ER_LOAD(0); ER_ADD(0); ER_LOAD(1); ER_STORE(0); ER_ADD(1); ER_STORE(1);
	v_lshlrev_b32_e32 v72, 16, v186
	v_and_b32_e32 v73, 0xffff0000, v186
	v_lshlrev_b32_e32 v74, 16, v187
	v_and_b32_e32 v75, 0xffff0000, v187
	v_addc_co_u32_e32 v99, vcc, 0, v147, vcc
	v_pk_add_f32 v[104:105], v[70:71], v[74:75]
	v_pk_add_f32 v[108:109], v[68:69], v[72:73]
	global_load_dwordx4 v[76:79], v[98:99], off
	global_load_dwordx4 v[72:75], v[98:99], off offset:256
	v_add_co_u32_e32 v96, vcc, s68, v146
	v_lshlrev_b32_e32 v68, 16, v188
	v_and_b32_e32 v69, 0xffff0000, v188
	v_lshlrev_b32_e32 v70, 16, v189
	v_and_b32_e32 v71, 0xffff0000, v189
	v_addc_co_u32_e32 v97, vcc, 0, v147, vcc
	v_pk_add_f32 v[106:107], v[66:67], v[70:71]
	v_pk_add_f32 v[112:113], v[64:65], v[68:69]
	global_load_dwordx4 v[68:71], v[96:97], off
	global_load_dwordx4 v[64:67], v[96:97], off offset:256
	s_nop 0
	global_store_dwordx4 v[146:147], v[166:169], off
	s_nop 1
	v_mul_f32_e32 v166, v199, v199
	v_mul_f32_e32 v167, v195, v195
	v_fmac_f32_e32 v166, v198, v198
	v_fmac_f32_e32 v167, v194, v194
	v_add_f32_e32 v166, v166, v167
	v_mul_f32_e32 v167, v175, v175
	v_fmac_f32_e32 v167, v174, v174
	v_add_f32_e32 v166, v167, v166
	v_mul_f32_e32 v167, v201, v201
	v_fmac_f32_e32 v167, v200, v200
	v_add_f32_e32 v170, v167, v166
	v_cvt_pk_bf16_f32 v166, v190, v191
	v_cvt_pk_bf16_f32 v167, v202, v203
	v_cvt_pk_bf16_f32 v168, v192, v193
	v_cvt_pk_bf16_f32 v169, v208, v209
	global_store_dwordx4 v[146:147], v[166:169], off offset:256
	v_mul_f32_e32 v146, v191, v191
	v_mul_f32_e32 v147, v203, v203
	v_fmac_f32_e32 v146, v190, v190
	v_fmac_f32_e32 v147, v202, v202
	v_add_f32_e32 v146, v146, v147
	v_mul_f32_e32 v147, v193, v193
	v_fmac_f32_e32 v147, v192, v192
	v_add_f32_e32 v146, v147, v146
	v_mul_f32_e32 v147, v209, v209
	v_fmac_f32_e32 v147, v208, v208
	v_cvt_pk_bf16_f32 v166, v212, v213
	v_add_f32_e32 v146, v147, v146
	v_cvt_pk_bf16_f32 v167, v210, v211
	v_cvt_pk_bf16_f32 v168, v216, v217
	v_cvt_pk_bf16_f32 v169, v214, v215
	global_store_dwordx4 v[144:145], v[166:169], off
	v_mul_f32_e32 v147, v213, v213
	v_fmac_f32_e32 v147, v212, v212
	v_mul_f32_e32 v166, v211, v211
	v_fmac_f32_e32 v166, v210, v210
	v_add_f32_e32 v147, v147, v166
	v_mul_f32_e32 v166, v217, v217
	v_fmac_f32_e32 v166, v216, v216
	v_add_f32_e32 v147, v166, v147
	v_mul_f32_e32 v166, v215, v215
	v_fmac_f32_e32 v166, v214, v214
	v_add_f32_e32 v147, v166, v147
	v_cvt_pk_bf16_f32 v166, v160, v161
	v_cvt_pk_bf16_f32 v167, v158, v159
	v_cvt_pk_bf16_f32 v168, v218, v219
	v_cvt_pk_bf16_f32 v169, v154, v155
	global_store_dwordx4 v[144:145], v[166:169], off offset:256
	v_mul_f32_e32 v144, v161, v161
	v_mul_f32_e32 v145, v159, v159
	v_fmac_f32_e32 v144, v160, v160
	v_fmac_f32_e32 v145, v158, v158
	v_add_f32_e32 v144, v144, v145
	v_mul_f32_e32 v145, v219, v219
	v_fmac_f32_e32 v145, v218, v218
	v_add_f32_e32 v144, v145, v144
	v_mul_f32_e32 v145, v155, v155
	v_fmac_f32_e32 v145, v154, v154
	v_add_f32_e32 v144, v145, v144
	v_add_f32_e32 v144, v147, v144
	v_mul_f32_e32 v145, v153, v153
	v_mul_f32_e32 v147, v149, v149
	v_cvt_pk_bf16_f32 v160, v126, v127
	v_fmac_f32_e32 v145, v152, v152
	v_fmac_f32_e32 v147, v148, v148
	v_mul_f32_e32 v127, v127, v127
	v_cvt_pk_bf16_f32 v161, v118, v119
	v_add_f32_e32 v145, v145, v147
	v_fmac_f32_e32 v127, v126, v126
	v_mul_f32_e32 v119, v119, v119
	v_add_f32_e32 v126, v127, v145
	v_fmac_f32_e32 v119, v118, v118
	v_cvt_pk_bf16_f32 v158, v152, v153
	v_add_f32_e32 v118, v119, v126
	v_cvt_pk_bf16_f32 v153, v120, v121
	v_mul_f32_e32 v119, v151, v151
	v_mul_f32_e32 v121, v121, v121
	v_fmac_f32_e32 v119, v150, v150
	v_fmac_f32_e32 v121, v120, v120
	v_mul_f32_e32 v120, v157, v157
	v_add_f32_e32 v119, v119, v121
	v_fmac_f32_e32 v120, v156, v156
	v_add_f32_e32 v119, v120, v119
	v_mul_f32_e32 v120, v125, v125
	v_cvt_pk_bf16_f32 v155, v124, v125
	v_fmac_f32_e32 v120, v124, v124
	v_cvt_pk_bf16_f32 v124, v116, v117
	v_cvt_pk_bf16_f32 v125, v110, v111
	v_mul_f32_e32 v117, v117, v117
	v_mul_f32_e32 v111, v111, v111
	v_fmac_f32_e32 v117, v116, v116
	v_fmac_f32_e32 v111, v110, v110
	v_add_f32_e32 v110, v117, v111
	v_mul_f32_e32 v111, v123, v123
	v_fmac_f32_e32 v111, v122, v122
	v_add_f32_e32 v110, v111, v110
	v_mul_f32_e32 v111, v115, v115
	v_cvt_pk_bf16_f32 v127, v114, v115
	v_fmac_f32_e32 v111, v114, v114
	v_cvt_pk_bf16_f32 v114, v108, v109
	v_cvt_pk_bf16_f32 v115, v104, v105
	v_mul_f32_e32 v109, v109, v109
	v_mul_f32_e32 v105, v105, v105
	v_fmac_f32_e32 v109, v108, v108
	v_fmac_f32_e32 v105, v104, v104
	v_add_f32_e32 v104, v109, v105
	v_mul_f32_e32 v105, v113, v113
	v_fmac_f32_e32 v105, v112, v112
	v_add_f32_e32 v104, v105, v104
	v_mul_f32_e32 v105, v107, v107
	v_fmac_f32_e32 v105, v106, v106
	v_add_f32_e32 v110, v111, v110
	v_add_f32_e32 v104, v105, v104
	v_cvt_pk_bf16_f32 v117, v106, v107
	v_add_f32_e32 v106, v110, v104
	s_waitcnt vmcnt(11)
	v_lshlrev_b32_e32 v104, 16, v92
	v_and_b32_e32 v105, 0xffff0000, v92
	v_lshlrev_b32_e32 v92, 16, v93
	v_and_b32_e32 v93, 0xffff0000, v93
	v_pk_add_f32 v[62:63], v[62:63], v[92:93]
	v_lshlrev_b32_e32 v92, 16, v94
	v_and_b32_e32 v93, 0xffff0000, v94
	v_pk_add_f32 v[56:57], v[56:57], v[92:93]
	s_waitcnt vmcnt(10)
	v_lshlrev_b32_e32 v92, 16, v88
	v_and_b32_e32 v93, 0xffff0000, v88
	v_lshlrev_b32_e32 v88, 16, v89
	v_and_b32_e32 v89, 0xffff0000, v89
	v_pk_add_f32 v[50:51], v[50:51], v[88:89]
	v_lshlrev_b32_e32 v88, 16, v90
	v_and_b32_e32 v89, 0xffff0000, v90
	v_pk_add_f32 v[40:41], v[40:41], v[88:89]
	s_waitcnt vmcnt(9)
	v_lshlrev_b32_e32 v88, 16, v84
	v_and_b32_e32 v89, 0xffff0000, v84
	v_lshlrev_b32_e32 v84, 16, v85
	v_and_b32_e32 v85, 0xffff0000, v85
	v_pk_add_f32 v[54:55], v[54:55], v[84:85]
	v_lshlrev_b32_e32 v84, 16, v86
	v_and_b32_e32 v85, 0xffff0000, v86
	v_pk_add_f32 v[44:45], v[44:45], v[84:85]
	s_waitcnt vmcnt(8)
	v_lshlrev_b32_e32 v84, 16, v80
	v_and_b32_e32 v85, 0xffff0000, v80
	v_lshlrev_b32_e32 v80, 16, v81
	v_and_b32_e32 v81, 0xffff0000, v81
	v_pk_add_f32 v[34:35], v[34:35], v[80:81]
	v_lshlrev_b32_e32 v80, 16, v82
	v_and_b32_e32 v81, 0xffff0000, v82
	v_pk_add_f32 v[24:25], v[24:25], v[80:81]
	s_waitcnt vmcnt(7)
	v_lshlrev_b32_e32 v80, 16, v76
	v_and_b32_e32 v81, 0xffff0000, v76
	v_lshlrev_b32_e32 v76, 16, v77
	v_and_b32_e32 v77, 0xffff0000, v77
	v_pk_add_f32 v[38:39], v[38:39], v[76:77]
	v_lshlrev_b32_e32 v76, 16, v78
	v_and_b32_e32 v77, 0xffff0000, v78
	v_pk_add_f32 v[28:29], v[28:29], v[76:77]
	s_waitcnt vmcnt(6)
	v_lshlrev_b32_e32 v76, 16, v72
	v_and_b32_e32 v77, 0xffff0000, v72
	v_lshlrev_b32_e32 v72, 16, v73
	v_and_b32_e32 v73, 0xffff0000, v73
	v_pk_add_f32 v[18:19], v[18:19], v[72:73]
	v_lshlrev_b32_e32 v72, 16, v74
	v_and_b32_e32 v73, 0xffff0000, v74
	v_lshlrev_b32_e32 v74, 16, v75
	v_and_b32_e32 v75, 0xffff0000, v75
	v_pk_add_f32 v[74:75], v[10:11], v[74:75]
	v_pk_add_f32 v[72:73], v[8:9], v[72:73]
	s_waitcnt vmcnt(5)
	v_lshlrev_b32_e32 v10, 16, v68
	v_and_b32_e32 v11, 0xffff0000, v68
	v_lshlrev_b32_e32 v8, 16, v69
	v_and_b32_e32 v9, 0xffff0000, v69
	v_pk_add_f32 v[8:9], v[22:23], v[8:9]
	v_pk_add_f32 v[20:21], v[20:21], v[10:11]
	v_lshlrev_b32_e32 v10, 16, v70
	v_and_b32_e32 v11, 0xffff0000, v70
	v_lshlrev_b32_e32 v22, 16, v71
	v_and_b32_e32 v23, 0xffff0000, v71
	v_pk_add_f32 v[14:15], v[14:15], v[22:23]
	v_pk_add_f32 v[22:23], v[12:13], v[10:11]
	s_waitcnt vmcnt(4)
	v_lshlrev_b32_e32 v10, 16, v64
	v_and_b32_e32 v11, 0xffff0000, v64
	v_lshlrev_b32_e32 v12, 16, v65
	v_and_b32_e32 v13, 0xffff0000, v65
	v_pk_add_f32 v[4:5], v[4:5], v[10:11]
	v_lshlrev_b32_e32 v10, 16, v66
	v_and_b32_e32 v11, 0xffff0000, v66
	v_pk_add_f32 v[60:61], v[60:61], v[104:105]
	v_lshlrev_b32_e32 v94, 16, v95
	v_and_b32_e32 v95, 0xffff0000, v95
	v_pk_add_f32 v[6:7], v[6:7], v[12:13]
	v_lshlrev_b32_e32 v12, 16, v67
	v_and_b32_e32 v13, 0xffff0000, v67
	v_pk_add_f32 v[0:1], v[0:1], v[10:11]
	v_cvt_pk_bf16_f32 v10, v60, v61
	v_cvt_pk_bf16_f32 v11, v62, v63
	v_pk_add_f32 v[58:59], v[58:59], v[94:95]
	v_pk_add_f32 v[2:3], v[2:3], v[12:13]
	v_cvt_pk_bf16_f32 v12, v56, v57
	v_cvt_pk_bf16_f32 v13, v58, v59
	global_store_dwordx4 v[102:103], v[10:13], off
	v_pk_add_f32 v[48:49], v[48:49], v[92:93]
	v_lshlrev_b32_e32 v90, 16, v91
	v_mul_f32_e32 v10, v61, v61
	v_mul_f32_e32 v11, v63, v63
	v_fmac_f32_e32 v10, v60, v60
	v_fmac_f32_e32 v11, v62, v62
	v_add_f32_e32 v10, v10, v11
	v_mul_f32_e32 v11, v57, v57
	v_fmac_f32_e32 v11, v56, v56
	v_add_f32_e32 v10, v11, v10
	v_mul_f32_e32 v11, v59, v59
	v_fmac_f32_e32 v11, v58, v58
	v_and_b32_e32 v91, 0xffff0000, v91
	v_add_f32_e32 v56, v11, v10
	v_cvt_pk_bf16_f32 v10, v48, v49
	v_cvt_pk_bf16_f32 v11, v50, v51
	v_pk_add_f32 v[42:43], v[42:43], v[90:91]
	v_cvt_pk_bf16_f32 v12, v40, v41
	v_pk_add_f32 v[52:53], v[52:53], v[88:89]
	v_cvt_pk_bf16_f32 v13, v42, v43
	global_store_dwordx4 v[102:103], v[10:13], off offset:256
	v_lshlrev_b32_e32 v86, 16, v87
	v_and_b32_e32 v87, 0xffff0000, v87
	v_mul_f32_e32 v10, v49, v49
	v_mul_f32_e32 v11, v51, v51
	v_fmac_f32_e32 v10, v48, v48
	v_fmac_f32_e32 v11, v50, v50
	v_add_f32_e32 v10, v10, v11
	v_mul_f32_e32 v11, v41, v41
	v_fmac_f32_e32 v11, v40, v40
	v_add_f32_e32 v10, v11, v10
	v_mul_f32_e32 v11, v43, v43
	v_fmac_f32_e32 v11, v42, v42
	v_add_f32_e32 v10, v11, v10
	v_add_f32_e32 v40, v56, v10
	v_cvt_pk_bf16_f32 v10, v52, v53
	v_cvt_pk_bf16_f32 v11, v54, v55
	v_pk_add_f32 v[46:47], v[46:47], v[86:87]
	v_cvt_pk_bf16_f32 v12, v44, v45
	v_pk_add_f32 v[32:33], v[32:33], v[84:85]
	v_cvt_pk_bf16_f32 v13, v46, v47
	global_store_dwordx4 v[100:101], v[10:13], off
	v_lshlrev_b32_e32 v82, 16, v83
	v_and_b32_e32 v83, 0xffff0000, v83
	v_mul_f32_e32 v10, v53, v53
	v_mul_f32_e32 v11, v55, v55
	v_fmac_f32_e32 v10, v52, v52
	v_fmac_f32_e32 v11, v54, v54
	v_add_f32_e32 v10, v10, v11
	v_mul_f32_e32 v11, v45, v45
	v_fmac_f32_e32 v11, v44, v44
	v_add_f32_e32 v10, v11, v10
	v_mul_f32_e32 v11, v47, v47
	v_fmac_f32_e32 v11, v46, v46
	v_add_f32_e32 v41, v11, v10
	v_cvt_pk_bf16_f32 v10, v32, v33
	v_cvt_pk_bf16_f32 v11, v34, v35
	v_pk_add_f32 v[26:27], v[26:27], v[82:83]
	v_cvt_pk_bf16_f32 v12, v24, v25
	v_pk_add_f32 v[36:37], v[36:37], v[80:81]
	v_cvt_pk_bf16_f32 v13, v26, v27
	global_store_dwordx4 v[100:101], v[10:13], off offset:256
	v_lshlrev_b32_e32 v78, 16, v79
	v_and_b32_e32 v79, 0xffff0000, v79
	v_mul_f32_e32 v10, v33, v33
	v_mul_f32_e32 v11, v35, v35
	v_fmac_f32_e32 v10, v32, v32
	v_fmac_f32_e32 v11, v34, v34
	v_add_f32_e32 v10, v10, v11
	v_mul_f32_e32 v11, v25, v25
	v_fmac_f32_e32 v11, v24, v24
	v_add_f32_e32 v10, v11, v10
	v_mul_f32_e32 v11, v27, v27
	v_fmac_f32_e32 v11, v26, v26
	v_add_f32_e32 v10, v11, v10
	v_add_f32_e32 v24, v41, v10
	v_cvt_pk_bf16_f32 v10, v36, v37
	v_cvt_pk_bf16_f32 v11, v38, v39
	v_pk_add_f32 v[30:31], v[30:31], v[78:79]
	v_cvt_pk_bf16_f32 v12, v28, v29
	v_pk_add_f32 v[16:17], v[16:17], v[76:77]
	v_cvt_pk_bf16_f32 v13, v30, v31
; __device__ __forceinline__ void ssq_add(ssq_t* p, float v) { __hip_atomic_fetch_add(p, ssq_fix(v), __ATOMIC_RELAXED, __HIP_MEMORY_SCOPE_AGENT); }
; #define ER_LOAD(ai) _Pragma("unroll") for (int m = 0; m < 4; ++m) _Pragma("unroll") for (int bj = 0; bj < 2; ++bj) xv[m][bj] = *(const u32x4*)(x16 + base + (size_t)((ai) * HALF + m * 16) * D + bj * HALF);
; #define ER_ADD(ai) _Pragma("unroll") for (int m = 0; m < 4; ++m) _Pragma("unroll") for (int bj = 0; bj < 2; ++bj) { const u32x4 w = xv[m][bj]; \
;             acc[ai][bj][m][0] += (f32x4){h_lo(w.x), h_hi(w.x), h_lo(w.y), h_hi(w.y)}; acc[ai][bj][m][1] += (f32x4){h_lo(w.z), h_hi(w.z), h_lo(w.w), h_hi(w.w)}; }
;     __device__ __forceinline__ void operator()(Acc& acc, const Unit& u, int wr, int wc, int fr, int fq) const {
;     ...
;         ER_LOAD(0); ER_ADD(0); ER_LOAD(1); ER_STORE(0); ER_ADD(1); ER_STORE(1);
;     ...
; #pragma unroll
;         for (int q = 0; q < 8; ++q) { ssv[q] += __shfl_xor(ssv[q], 16); }
; #pragma unroll
;         for (int q = 0; q < 8; ++q) { ssv[q] += __shfl_xor(ssv[q], 32); }
;         if (fq == 0) {
; #pragma unroll
;             for (int q = 0; q < 8; ++q) ssq_add(ssq_out + row0 + (q >> 2) * HALF + (q & 3) * 16, ssv[q]);
	global_store_dwordx4 v[98:99], v[10:13], off
	v_add_f32_e32 v119, v120, v119
	v_add_f32_e32 v146, v170, v146
	v_mul_f32_e32 v10, v37, v37
	v_mul_f32_e32 v11, v39, v39
	v_fmac_f32_e32 v10, v36, v36
	v_fmac_f32_e32 v11, v38, v38
	v_add_f32_e32 v10, v10, v11
	v_mul_f32_e32 v11, v29, v29
	v_fmac_f32_e32 v11, v28, v28
	v_add_f32_e32 v10, v11, v10
	v_mul_f32_e32 v11, v31, v31
	v_fmac_f32_e32 v11, v30, v30
	v_add_f32_e32 v25, v11, v10
	v_cvt_pk_bf16_f32 v10, v16, v17
	v_cvt_pk_bf16_f32 v11, v18, v19
	v_cvt_pk_bf16_f32 v12, v72, v73
	v_cvt_pk_bf16_f32 v13, v74, v75
	global_store_dwordx4 v[98:99], v[10:13], off offset:256
	v_add_f32_e32 v118, v118, v119
	v_cvt_pk_bf16_f32 v159, v148, v149
	global_store_dwordx4 v[142:143], v[158:161], off
	v_mul_f32_e32 v10, v17, v17
	v_mul_f32_e32 v11, v19, v19
	v_fmac_f32_e32 v10, v16, v16
	v_fmac_f32_e32 v11, v18, v18
	v_add_f32_e32 v10, v10, v11
	v_mul_f32_e32 v11, v73, v73
	v_fmac_f32_e32 v11, v72, v72
	v_add_f32_e32 v10, v11, v10
	v_mul_f32_e32 v11, v75, v75
	v_fmac_f32_e32 v11, v74, v74
	v_add_f32_e32 v10, v11, v10
	v_add_f32_e32 v16, v25, v10
	v_cvt_pk_bf16_f32 v10, v20, v21
	v_cvt_pk_bf16_f32 v11, v8, v9
	v_cvt_pk_bf16_f32 v12, v22, v23
	v_cvt_pk_bf16_f32 v13, v14, v15
	global_store_dwordx4 v[96:97], v[10:13], off
	v_mul_f32_e32 v9, v9, v9
	v_fmac_f32_e32 v9, v8, v8
	v_mul_f32_e32 v10, v21, v21
	v_fmac_f32_e32 v10, v20, v20
	v_add_f32_e32 v8, v10, v9
	v_mul_f32_e32 v9, v23, v23
	v_fmac_f32_e32 v9, v22, v22
	v_add_f32_e32 v8, v9, v8
	v_mul_f32_e32 v9, v15, v15
	v_fmac_f32_e32 v9, v14, v14
	v_and_b32_e32 v10, 64, v204
	v_add_f32_e32 v8, v9, v8
	v_xor_b32_e32 v9, 16, v204
	v_add_u32_e32 v13, 64, v10
	v_cvt_pk_bf16_f32 v22, v4, v5
	v_mul_f32_e32 v5, v5, v5
	v_cmp_lt_i32_e32 vcc, v9, v13
	v_fmac_f32_e32 v5, v4, v4
	v_mul_f32_e32 v4, v7, v7
	v_cndmask_b32_e32 v9, v204, v9, vcc
	v_fmac_f32_e32 v4, v6, v6
	v_lshlrev_b32_e32 v9, 2, v9
	v_add_f32_e32 v4, v5, v4
	v_mul_f32_e32 v5, v1, v1
	ds_bpermute_b32 v10, v9, v146
	ds_bpermute_b32 v11, v9, v144
	ds_bpermute_b32 v12, v9, v118
	v_fmac_f32_e32 v5, v0, v0
	v_add_f32_e32 v4, v5, v4
	v_mul_f32_e32 v5, v3, v3
	v_fmac_f32_e32 v5, v2, v2
	v_add_f32_e32 v4, v5, v4
	v_add_f32_e32 v14, v8, v4
	s_waitcnt lgkmcnt(2)
	v_add_f32_e32 v4, v146, v10
	s_waitcnt lgkmcnt(1)
	v_add_f32_e32 v5, v144, v11
	s_waitcnt lgkmcnt(0)
	v_add_f32_e32 v8, v118, v12
	ds_bpermute_b32 v10, v9, v106
	ds_bpermute_b32 v11, v9, v40
	ds_bpermute_b32 v12, v9, v24
	ds_bpermute_b32 v15, v9, v16
	ds_bpermute_b32 v17, v9, v14
	s_waitcnt lgkmcnt(4)
	v_add_f32_e32 v9, v106, v10
	s_waitcnt lgkmcnt(3)
	v_add_f32_e32 v10, v40, v11
	s_waitcnt lgkmcnt(2)
	v_add_f32_e32 v11, v24, v12
	s_waitcnt lgkmcnt(1)
	v_add_f32_e32 v12, v16, v15
	v_xor_b32_e32 v15, 32, v204
	v_cmp_lt_i32_e32 vcc, v15, v13
	s_waitcnt lgkmcnt(0)
	v_add_f32_e32 v14, v14, v17
	v_cvt_pk_bf16_f32 v152, v150, v151
	v_cvt_pk_bf16_f32 v154, v156, v157
	global_store_dwordx4 v[142:143], v[152:155], off offset:256
	v_cndmask_b32_e32 v13, v204, v15, vcc
	v_lshlrev_b32_e32 v21, 2, v13
	ds_bpermute_b32 v13, v21, v4
	ds_bpermute_b32 v15, v21, v5
	ds_bpermute_b32 v16, v21, v8
	ds_bpermute_b32 v17, v21, v9
	ds_bpermute_b32 v18, v21, v10
	ds_bpermute_b32 v19, v21, v11
	ds_bpermute_b32 v20, v21, v12
	ds_bpermute_b32 v21, v21, v14
	v_cvt_pk_bf16_f32 v126, v122, v123
	global_store_dwordx4 v[140:141], v[124:127], off
	v_cvt_pk_bf16_f32 v116, v112, v113
	global_store_dwordx4 v[140:141], v[114:117], off offset:256
	v_cvt_pk_bf16_f32 v23, v6, v7
	v_cvt_pk_bf16_f32 v24, v0, v1
	v_cvt_pk_bf16_f32 v25, v2, v3
	global_store_dwordx4 v[96:97], v[22:25], off offset:256
	s_and_saveexec_b64 s[0:1], s[4:5]
	s_mov_b32 s37, 0x18000
	s_mov_b32 s36, 0x8000
	s_mov_b32 s35, 0x30000
	s_mov_b32 s34, 0x40000
	s_mov_b32 s63, 0x4c000
	s_cbranch_execz .LBB0_800
	s_waitcnt lgkmcnt(7)
	v_add_f32_e32 v4, v4, v13
	s_waitcnt lgkmcnt(6)
	v_add_f32_e32 v5, v5, v15
	v_fma_f32 v4, v4, s67, 0.5
	s_waitcnt lgkmcnt(5)
	v_add_f32_e32 v8, v8, v16
	v_cvt_u32_f32_e32 v4, v4
	v_fma_f32 v5, v5, s67, 0.5
	s_waitcnt lgkmcnt(4)
	v_add_f32_e32 v9, v9, v17
	v_cvt_u32_f32_e32 v5, v5
	v_fma_f32 v8, v8, s67, 0.5
	v_cvt_u32_f32_e32 v8, v8
	v_fma_f32 v9, v9, s67, 0.5
	s_waitcnt lgkmcnt(3)
	v_add_f32_e32 v7, v10, v18
	v_lshl_add_u64 v[0:1], v[138:139], 2, s[10:11]
	v_cvt_u32_f32_e32 v9, v9
	s_waitcnt lgkmcnt(2)
	v_add_f32_e32 v6, v11, v19
	global_atomic_add v[0:1], v4, off
	global_atomic_add v[0:1], v5, off offset:64
	global_atomic_add v[0:1], v8, off offset:128
	global_atomic_add v[0:1], v9, off offset:192
	v_fma_f32 v4, v7, s67, 0.5
	s_waitcnt lgkmcnt(1)
	v_add_f32_e32 v3, v12, v20
	v_cvt_u32_f32_e32 v4, v4
	v_fma_f32 v5, v6, s67, 0.5
	s_waitcnt lgkmcnt(0)
	v_add_f32_e32 v2, v14, v21
	v_cvt_u32_f32_e32 v5, v5
	v_fma_f32 v3, v3, s67, 0.5
	v_cvt_u32_f32_e32 v3, v3
	v_fma_f32 v2, v2, s67, 0.5
	v_cvt_u32_f32_e32 v2, v2
	global_atomic_add v[0:1], v4, off offset:512
	global_atomic_add v[0:1], v5, off offset:576
	global_atomic_add v[0:1], v3, off offset:640
	global_atomic_add v[0:1], v2, off offset:704
